# stack: EpiResid prefetch + GEMM prologue K-tile-1 loads issued before the K-tile-0 wait + K-loop back-edge rotation + barrier leader release-first
# baseline (speedup 1.0000x reference)
; #define PG8_STAGE(bufoff, gbase, voff) do { _Pragma("unroll") for (int _i = 0; _i < 2; ++_i) \
;         __builtin_amdgcn_global_load_lds((const unsigned*)((const char*)(gbase) + (voff)[_i]), (PG8_LAS unsigned*)(lds + (bufoff) + ldsw + _i * 8192), 16, 0, 0); } while (0)
; #define PG8_WAIT_V(n) asm volatile("s_waitcnt vmcnt(" #n ")" ::: "memory")
; #define PG8_BAR __builtin_amdgcn_s_barrier()
; template <class Epi, class Sched, bool ALIGN_EPI = false, bool SP2 = false>
; __device__ __forceinline__ void gemm_phase(PG8_LAS unsigned char* lds, const Gemm g, const Sched& S, const Epi& E, int tid_in) {
;     ...
;         PG8_STAGE(PG8_SB(0, 0), cB, voffB); PG8_STAGE(PG8_SB(0, 1), cB + hstep, voffB); PG8_STAGE(PG8_SA(0, 0), cA, voffA); PG8_STAGE(PG8_SA(0, 1), cA + hstep, voffA);
;         if (wr == 1) PG8_BAR;
;         PG8_WAIT_V(2); PG8_BAR;
;         PG8_STAGE(PG8_SB(1, 0), cB + kstep, voffB); PG8_STAGE(PG8_SA(1, 0), cA + kstep, voffA); PG8_STAGE(PG8_SB(1, 1), cB + hstep + kstep, voffB);
;         PG8_WAIT_V(6); PG8_BAR;
.LBB0_177:
	v_readlane_b32 s16, v254, 36
	s_add_i32 s16, s61, s16
	v_readlane_b32 s17, v254, 37
	s_lshl_b32 s16, s16, 20
	s_and_b32 s16, s16, 0x100000
	v_readlane_b32 s17, v254, 61
	s_add_u32 s16, s17, s16
	v_readlane_b32 s17, v254, 62
	s_addc_u32 s17, s17, 0
	s_add_i32 m0, s48, 0x18000
	v_lshl_add_u64 v[8:9], v[8:9], 0, s[52:53]
	global_load_lds_dwordx4 v[8:9], off
	v_lshl_add_u64 v[4:5], v[4:5], 0, s[52:53]
	s_add_i32 m0, s48, 0x1a000
	s_add_i32 s58, s48, 0x8000
	global_load_lds_dwordx4 v[4:5], off
	v_lshl_add_u64 v[4:5], v[6:7], 0, s[52:53]
	s_mov_b32 m0, s58
	s_add_i32 s66, s48, 0xa000
	global_load_lds_dwordx4 v[4:5], off
	v_lshl_add_u64 v[4:5], v[10:11], 0, s[52:53]
	s_mov_b32 m0, s66
	v_lshl_add_u64 v[2:3], v[2:3], 0, s[52:53]
	global_load_lds_dwordx4 v[4:5], off
	s_add_i32 m0, s48, 0x1c000
	v_lshl_add_u64 v[0:1], v[0:1], 0, s[52:53]
	global_load_lds_dwordx4 v[2:3], off
	s_add_i32 m0, s48, 0x1e000
	v_bfe_u32 v148, v12, 4, 2
	global_load_lds_dwordx4 v[0:1], off
	s_waitcnt vmcnt(8)
	s_barrier
	s_lshr_b32 s3, s3, 26
	v_and_b32_e32 v149, 15, v12
	s_add_i32 s3, s2, s3
	v_lshlrev_b32_e32 v0, 4, v148
	v_lshlrev_b32_e32 v1, 2, v12
	s_ashr_i32 s70, s3, 6
	v_lshl_or_b32 v0, v149, 6, v0
	s_lshl_b32 s3, s9, 13
	v_and_b32_e32 v1, 32, v1
	v_bitop3_b32 v2, v0, s3, v1 bitop3:0xde
	s_lshl_b32 s3, s5, 5
	s_and_b32 s74, s3, 0x60
	s_lshl_b32 s3, s74, 7
	s_lshl_b32 s71, s9, 6
	v_bitop3_b32 v150, v0, s3, v1 bitop3:0xde
	v_add_u32_e32 v0, v18, v16
	s_cmp_gt_i32 s2, 63
	v_add_lshl_u32 v0, v0, v17, 1
	v_mov_b32_e32 v1, v137
	s_waitcnt vmcnt(6)
	s_cselect_b64 s[24:25], -1, 0
	s_add_i32 s77, s70, -2
	v_lshl_add_u64 v[134:135], s[10:11], 0, v[0:1]
	v_add_u32_e32 v0, v15, v13
	s_cmpk_lt_u32 s4, 0x100
	v_add_lshl_u32 v0, v0, v14, 1
	s_cselect_b64 s[26:27], -1, 0
	s_ashr_i32 s9, s8, 31
	v_lshl_add_u64 v[140:141], s[10:11], 0, v[0:1]
	s_mov_b32 s30, 0
	v_add_u32_e32 v151, 0, v2
	s_barrier
	s_branch .LBB0_180

; #define PG8_STAGE(bufoff, gbase, voff) do { _Pragma("unroll") for (int _i = 0; _i < 2; ++_i) \
;         __builtin_amdgcn_global_load_lds((const unsigned*)((const char*)(gbase) + (voff)[_i]), (PG8_LAS unsigned*)(lds + (bufoff) + ldsw + _i * 8192), 16, 0, 0); } while (0)
; #define PG8_LDA(dst, b, h) do { _Pragma("unroll") for (int m = 0; m < 4; ++m) _Pragma("unroll") for (int k = 0; k < 2; ++k) dst[m][k] = *(const PG8_LAS bf16x8*)(lds + PG8_SA(b, h) + aoff + m * 2048 + k * 1024); } while (0)
; #define PG8_LDB(dst, b, h) do { _Pragma("unroll") for (int n = 0; n < 2; ++n) _Pragma("unroll") for (int k = 0; k < 2; ++k) dst[n][k] = *(const PG8_LAS bf16x8*)(lds + PG8_SB(b, h) + boff + n * 2048 + k * 1024); } while (0)
; #define PG8_MMA(ai, bj, At, Bt) do { __builtin_amdgcn_s_setprio(1); _Pragma("unroll") for (int m = 0; m < 4; ++m) _Pragma("unroll") for (int n = 0; n < 2; ++n) _Pragma("unroll") for (int k = 0; k < 2; ++k) \
;         acc[ai][bj][m][n] = __builtin_amdgcn_mfma_f32_16x16x32_bf16(Bt[n][k], At[m][k], acc[ai][bj][m][n], 0, 0, 0); __builtin_amdgcn_s_setprio(0); } while (0)
; #define PG8_WAIT_V(n) asm volatile("s_waitcnt vmcnt(" #n ")" ::: "memory")
; #define PG8_WAIT_L(n) asm volatile("s_waitcnt lgkmcnt(" #n ")" ::: "memory")
; #define PG8_BAR __builtin_amdgcn_s_barrier()
; #define PG8_SCHED __builtin_amdgcn_sched_barrier(0)
; template <class Epi, class Sched, bool ALIGN_EPI = false, bool SP2 = false>
; __device__ __forceinline__ void gemm_phase(PG8_LAS unsigned char* lds, const Gemm g, const Sched& S, const Epi& E, int tid_in) {
;     ...
;             PG8_LDB(B0, 0, 0); PG8_LDB(B1, 0, 1); PG8_SCHED; PG8_LDA(At, 0, 0); PG8_STAGE(PG8_SA(1, 1), a1 + hstep, voffA);
;             PG8_WAIT_V(8); PG8_WAIT_L(0); PG8_BAR; PG8_MMA(0, 0, At, B0); PG8_MMA(0, 1, At, B1); PG8_BAR; PG8_SCHED;
;             PG8_LDA(At, 0, 1); PG8_STAGE(PG8_SB(0, 0), b2, voffB); PG8_STAGE(PG8_SB(0, 1), b2 + hstep, voffB); PG8_STAGE(PG8_SA(0, 0), a2, voffA);
;             PG8_WAIT_V(8); PG8_WAIT_L(0); PG8_BAR; PG8_MMA(1, 0, At, B0); PG8_MMA(1, 1, At, B1); PG8_BAR; PG8_SCHED;
.LBB0_188:
	s_add_i32 s84, s40, 2
	s_add_u32 s85, s38, 0x80
	s_addc_u32 s41, s39, 0
	s_add_i32 s92, 0, 0x10000
	s_cmp_eq_u32 s77, s40
	s_cselect_b32 s41, s5, s41
	s_cselect_b32 s40, s4, s85
	v_add_u32_e32 v139, s92, v150
	s_cselect_b32 s91, s37, s83
	s_cselect_b32 s90, s36, s81
	s_add_i32 s85, 0, 0x14000
	ds_read_b128 v[142:145], v139
	ds_read_b128 v[152:155], v139 offset:1024
	ds_read_b128 v[156:159], v139 offset:2048
	ds_read_b128 v[160:163], v139 offset:3072
	v_add_u32_e32 v139, s85, v150
	ds_read_b128 v[172:175], v139
	ds_read_b128 v[176:179], v139 offset:1024
	ds_read_b128 v[180:183], v139 offset:2048
	ds_read_b128 v[184:187], v139 offset:3072
	v_lshl_add_u64 v[146:147], s[38:39], 0, v[134:135]
	s_add_i32 m0, s48, 0xc000
	ds_read_b128 v[188:191], v151
	ds_read_b128 v[192:195], v151 offset:1024
	ds_read_b128 v[196:199], v151 offset:2048
	ds_read_b128 v[200:203], v151 offset:3072
	ds_read_b128 v[204:207], v151 offset:4096
	ds_read_b128 v[208:211], v151 offset:5120
	ds_read_b128 v[212:215], v151 offset:6144
	ds_read_b128 v[216:219], v151 offset:7168
	global_load_lds_dwordx4 v[146:147], off
	v_lshl_add_u64 v[146:147], s[38:39], 0, v[140:141]
	s_add_i32 m0, s48, 0xe000
	s_nop 0
	global_load_lds_dwordx4 v[146:147], off
	s_waitcnt vmcnt(8)
	s_waitcnt lgkmcnt(0)
	s_barrier
	s_setprio 1
	s_waitcnt lgkmcnt(0)
	v_mfma_f32_16x16x32_bf16 v[124:127], v[142:145], v[188:191], v[124:127]
	v_mfma_f32_16x16x32_bf16 v[120:123], v[156:159], v[188:191], v[120:123]
	v_mfma_f32_16x16x32_bf16 v[108:111], v[142:145], v[196:199], v[108:111]
	v_mfma_f32_16x16x32_bf16 v[104:107], v[156:159], v[196:199], v[104:107]
	v_mfma_f32_16x16x32_bf16 v[92:95], v[142:145], v[204:207], v[92:95]
	v_mfma_f32_16x16x32_bf16 v[88:91], v[156:159], v[204:207], v[88:91]
	v_mfma_f32_16x16x32_bf16 v[76:79], v[142:145], v[212:215], v[76:79]
	v_mfma_f32_16x16x32_bf16 v[72:75], v[156:159], v[212:215], v[72:75]
	v_mfma_f32_16x16x32_bf16 v[124:127], v[152:155], v[192:195], v[124:127]
	v_mfma_f32_16x16x32_bf16 v[120:123], v[160:163], v[192:195], v[120:123]
	v_mfma_f32_16x16x32_bf16 v[108:111], v[152:155], v[200:203], v[108:111]
	v_mfma_f32_16x16x32_bf16 v[104:107], v[160:163], v[200:203], v[104:107]
	v_mfma_f32_16x16x32_bf16 v[92:95], v[152:155], v[208:211], v[92:95]
	v_mfma_f32_16x16x32_bf16 v[88:91], v[160:163], v[208:211], v[88:91]
	v_mfma_f32_16x16x32_bf16 v[76:79], v[152:155], v[216:219], v[76:79]
	v_mfma_f32_16x16x32_bf16 v[72:75], v[160:163], v[216:219], v[72:75]
	s_setprio 0
	s_setprio 1
	v_mfma_f32_16x16x32_bf16 v[116:119], v[172:175], v[188:191], v[116:119]
	v_mfma_f32_16x16x32_bf16 v[112:115], v[180:183], v[188:191], v[112:115]
	v_mfma_f32_16x16x32_bf16 v[100:103], v[172:175], v[196:199], v[100:103]
	v_mfma_f32_16x16x32_bf16 v[96:99], v[180:183], v[196:199], v[96:99]
	v_mfma_f32_16x16x32_bf16 v[84:87], v[172:175], v[204:207], v[84:87]
	v_mfma_f32_16x16x32_bf16 v[80:83], v[180:183], v[204:207], v[80:83]
	v_mfma_f32_16x16x32_bf16 v[68:71], v[172:175], v[212:215], v[68:71]
	v_mfma_f32_16x16x32_bf16 v[64:67], v[180:183], v[212:215], v[64:67]
	v_mfma_f32_16x16x32_bf16 v[116:119], v[176:179], v[192:195], v[116:119]
	v_mfma_f32_16x16x32_bf16 v[112:115], v[184:187], v[192:195], v[112:115]
	v_mfma_f32_16x16x32_bf16 v[100:103], v[176:179], v[200:203], v[100:103]
	v_mfma_f32_16x16x32_bf16 v[96:99], v[184:187], v[200:203], v[96:99]
	v_mfma_f32_16x16x32_bf16 v[84:87], v[176:179], v[208:211], v[84:87]
	v_mfma_f32_16x16x32_bf16 v[80:83], v[184:187], v[208:211], v[80:83]
	v_mfma_f32_16x16x32_bf16 v[68:71], v[176:179], v[216:219], v[68:71]
	v_mfma_f32_16x16x32_bf16 v[64:67], v[184:187], v[216:219], v[64:67]
	s_setprio 0
	s_barrier
	s_add_i32 s92, s92, s34
	v_lshl_add_u64 v[146:147], s[90:91], 0, v[136:137]
	s_mov_b32 m0, s92
	ds_read_b128 v[188:191], v151 offset:16384
	ds_read_b128 v[192:195], v151 offset:17408
	ds_read_b128 v[196:199], v151 offset:18432
	ds_read_b128 v[200:203], v151 offset:19456
	ds_read_b128 v[204:207], v151 offset:20480
	ds_read_b128 v[208:211], v151 offset:21504
	ds_read_b128 v[212:215], v151 offset:22528
	ds_read_b128 v[216:219], v151 offset:23552
	global_load_lds_dwordx4 v[146:147], off
	s_add_i32 m0, s92, 0x2000
	v_lshl_add_u64 v[164:165], s[90:91], 0, v[128:129]
	s_add_u32 s90, s90, s10
	s_addc_u32 s91, s91, s11
	s_add_i32 s85, s85, s34
	global_load_lds_dwordx4 v[164:165], off
	v_lshl_add_u64 v[220:221], s[90:91], 0, v[136:137]
	s_mov_b32 m0, s85
	v_lshl_add_u64 v[222:223], s[90:91], 0, v[128:129]
	global_load_lds_dwordx4 v[220:221], off
	s_add_i32 m0, s85, 0x2000
	v_lshl_add_u64 v[224:225], s[40:41], 0, v[132:133]
	global_load_lds_dwordx4 v[222:223], off
	s_mov_b32 m0, s48
	v_lshl_add_u64 v[226:227], s[40:41], 0, v[130:131]
	global_load_lds_dwordx4 v[224:225], off
	s_mov_b32 m0, s49
	s_nop 0
	global_load_lds_dwordx4 v[226:227], off
	s_waitcnt vmcnt(8)
	s_waitcnt lgkmcnt(0)
	s_barrier
; #define PG8_STAGE(bufoff, gbase, voff) do { _Pragma("unroll") for (int _i = 0; _i < 2; ++_i) \
;         __builtin_amdgcn_global_load_lds((const unsigned*)((const char*)(gbase) + (voff)[_i]), (PG8_LAS unsigned*)(lds + (bufoff) + ldsw + _i * 8192), 16, 0, 0); } while (0)
; #define PG8_LDA(dst, b, h) do { _Pragma("unroll") for (int m = 0; m < 4; ++m) _Pragma("unroll") for (int k = 0; k < 2; ++k) dst[m][k] = *(const PG8_LAS bf16x8*)(lds + PG8_SA(b, h) + aoff + m * 2048 + k * 1024); } while (0)
; #define PG8_LDB(dst, b, h) do { _Pragma("unroll") for (int n = 0; n < 2; ++n) _Pragma("unroll") for (int k = 0; k < 2; ++k) dst[n][k] = *(const PG8_LAS bf16x8*)(lds + PG8_SB(b, h) + boff + n * 2048 + k * 1024); } while (0)
; #define PG8_MMA(ai, bj, At, Bt) do { __builtin_amdgcn_s_setprio(1); _Pragma("unroll") for (int m = 0; m < 4; ++m) _Pragma("unroll") for (int n = 0; n < 2; ++n) _Pragma("unroll") for (int k = 0; k < 2; ++k) \
;         acc[ai][bj][m][n] = __builtin_amdgcn_mfma_f32_16x16x32_bf16(Bt[n][k], At[m][k], acc[ai][bj][m][n], 0, 0, 0); __builtin_amdgcn_s_setprio(0); } while (0)
; #define PG8_WAIT_V(n) asm volatile("s_waitcnt vmcnt(" #n ")" ::: "memory")
; #define PG8_WAIT_L(n) asm volatile("s_waitcnt lgkmcnt(" #n ")" ::: "memory")
; #define PG8_BAR __builtin_amdgcn_s_barrier()
; #define PG8_SCHED __builtin_amdgcn_sched_barrier(0)
; template <class Epi, class Sched, bool ALIGN_EPI = false, bool SP2 = false>
; __device__ __forceinline__ void gemm_phase(PG8_LAS unsigned char* lds, const Gemm g, const Sched& S, const Epi& E, int tid_in) {
;     ...
;             PG8_WAIT_V(8); PG8_WAIT_L(0); PG8_BAR; PG8_MMA(1, 0, At, B0); PG8_MMA(1, 1, At, B1); PG8_BAR; PG8_SCHED;
;             PG8_LDB(B0, 1, 0); PG8_LDB(B1, 1, 1); PG8_SCHED; PG8_LDA(At, 1, 0); PG8_STAGE(PG8_SA(0, 1), a2 + hstep, voffA);
;             PG8_WAIT_V(8); PG8_WAIT_L(0); PG8_BAR; PG8_MMA(0, 0, At, B0); PG8_MMA(0, 1, At, B1); PG8_BAR; PG8_SCHED;
	s_setprio 1
	s_waitcnt lgkmcnt(0)
	v_mfma_f32_16x16x32_bf16 v[60:63], v[142:145], v[188:191], v[60:63]
	v_mfma_f32_16x16x32_bf16 v[56:59], v[156:159], v[188:191], v[56:59]
	v_mfma_f32_16x16x32_bf16 v[44:47], v[142:145], v[196:199], v[44:47]
	v_mfma_f32_16x16x32_bf16 v[40:43], v[156:159], v[196:199], v[40:43]
	v_mfma_f32_16x16x32_bf16 v[28:31], v[142:145], v[204:207], v[28:31]
	v_mfma_f32_16x16x32_bf16 v[24:27], v[156:159], v[204:207], v[24:27]
	v_mfma_f32_16x16x32_bf16 v[12:15], v[142:145], v[212:215], v[12:15]
	v_mfma_f32_16x16x32_bf16 v[8:11], v[156:159], v[212:215], v[8:11]
	v_mfma_f32_16x16x32_bf16 v[60:63], v[152:155], v[192:195], v[60:63]
	v_mfma_f32_16x16x32_bf16 v[56:59], v[160:163], v[192:195], v[56:59]
	v_mfma_f32_16x16x32_bf16 v[44:47], v[152:155], v[200:203], v[44:47]
	v_mfma_f32_16x16x32_bf16 v[40:43], v[160:163], v[200:203], v[40:43]
	v_mfma_f32_16x16x32_bf16 v[28:31], v[152:155], v[208:211], v[28:31]
	v_mfma_f32_16x16x32_bf16 v[24:27], v[160:163], v[208:211], v[24:27]
	v_mfma_f32_16x16x32_bf16 v[12:15], v[152:155], v[216:219], v[12:15]
	v_mfma_f32_16x16x32_bf16 v[8:11], v[160:163], v[216:219], v[8:11]
	s_setprio 0
	s_setprio 1
	v_mfma_f32_16x16x32_bf16 v[52:55], v[172:175], v[188:191], v[52:55]
	v_mfma_f32_16x16x32_bf16 v[48:51], v[180:183], v[188:191], v[48:51]
	v_mfma_f32_16x16x32_bf16 v[36:39], v[172:175], v[196:199], v[36:39]
	v_mfma_f32_16x16x32_bf16 v[32:35], v[180:183], v[196:199], v[32:35]
	v_mfma_f32_16x16x32_bf16 v[20:23], v[172:175], v[204:207], v[20:23]
	v_mfma_f32_16x16x32_bf16 v[16:19], v[180:183], v[204:207], v[16:19]
	v_mfma_f32_16x16x32_bf16 v[4:7], v[172:175], v[212:215], v[4:7]
	v_mfma_f32_16x16x32_bf16 v[0:3], v[180:183], v[212:215], v[0:3]
	v_mfma_f32_16x16x32_bf16 v[52:55], v[176:179], v[192:195], v[52:55]
	v_mfma_f32_16x16x32_bf16 v[48:51], v[184:187], v[192:195], v[48:51]
	v_mfma_f32_16x16x32_bf16 v[36:39], v[176:179], v[200:203], v[36:39]
	v_mfma_f32_16x16x32_bf16 v[32:35], v[184:187], v[200:203], v[32:35]
	v_mfma_f32_16x16x32_bf16 v[20:23], v[176:179], v[208:211], v[20:23]
	v_mfma_f32_16x16x32_bf16 v[16:19], v[184:187], v[208:211], v[16:19]
	v_mfma_f32_16x16x32_bf16 v[4:7], v[176:179], v[216:219], v[4:7]
	v_mfma_f32_16x16x32_bf16 v[0:3], v[184:187], v[216:219], v[0:3]
	s_setprio 0
	s_barrier
	s_add_i32 s85, 0, 0x18000
	v_add_u32_e32 v139, s85, v150
	s_add_i32 s90, 0, 0x1c000
	ds_read_b128 v[142:145], v139
	ds_read_b128 v[152:155], v139 offset:1024
	ds_read_b128 v[156:159], v139 offset:2048
	ds_read_b128 v[160:163], v139 offset:3072
	v_add_u32_e32 v139, s90, v150
	ds_read_b128 v[172:175], v139
	ds_read_b128 v[176:179], v139 offset:1024
	ds_read_b128 v[180:183], v139 offset:2048
	ds_read_b128 v[184:187], v139 offset:3072
	s_add_u32 s40, s40, s10
	s_addc_u32 s41, s41, s11
	s_mov_b32 m0, s54
	v_lshl_add_u64 v[228:229], s[40:41], 0, v[132:133]
	ds_read_b128 v[188:191], v151 offset:32768
	ds_read_b128 v[192:195], v151 offset:33792
	ds_read_b128 v[196:199], v151 offset:34816
	ds_read_b128 v[200:203], v151 offset:35840
	ds_read_b128 v[204:207], v151 offset:36864
	ds_read_b128 v[208:211], v151 offset:37888
	ds_read_b128 v[212:215], v151 offset:38912
	ds_read_b128 v[216:219], v151 offset:39936
	global_load_lds_dwordx4 v[228:229], off
	v_lshl_add_u64 v[228:229], s[40:41], 0, v[130:131]
	s_mov_b32 m0, s55
	s_nop 0
	global_load_lds_dwordx4 v[228:229], off
	s_waitcnt vmcnt(8)
	s_waitcnt lgkmcnt(0)
	s_barrier
	s_setprio 1
	s_waitcnt lgkmcnt(0)
	v_mfma_f32_16x16x32_bf16 v[124:127], v[142:145], v[188:191], v[124:127]
	v_mfma_f32_16x16x32_bf16 v[120:123], v[156:159], v[188:191], v[120:123]
	v_mfma_f32_16x16x32_bf16 v[108:111], v[142:145], v[196:199], v[108:111]
	v_mfma_f32_16x16x32_bf16 v[104:107], v[156:159], v[196:199], v[104:107]
	v_mfma_f32_16x16x32_bf16 v[92:95], v[142:145], v[204:207], v[92:95]
	v_mfma_f32_16x16x32_bf16 v[88:91], v[156:159], v[204:207], v[88:91]
	v_mfma_f32_16x16x32_bf16 v[76:79], v[142:145], v[212:215], v[76:79]
	v_mfma_f32_16x16x32_bf16 v[72:75], v[156:159], v[212:215], v[72:75]
	v_mfma_f32_16x16x32_bf16 v[124:127], v[152:155], v[192:195], v[124:127]
	v_mfma_f32_16x16x32_bf16 v[120:123], v[160:163], v[192:195], v[120:123]
	v_mfma_f32_16x16x32_bf16 v[108:111], v[152:155], v[200:203], v[108:111]
	v_mfma_f32_16x16x32_bf16 v[104:107], v[160:163], v[200:203], v[104:107]
	v_mfma_f32_16x16x32_bf16 v[92:95], v[152:155], v[208:211], v[92:95]
	v_mfma_f32_16x16x32_bf16 v[88:91], v[160:163], v[208:211], v[88:91]
	v_mfma_f32_16x16x32_bf16 v[76:79], v[152:155], v[216:219], v[76:79]
	v_mfma_f32_16x16x32_bf16 v[72:75], v[160:163], v[216:219], v[72:75]
	s_setprio 0
	s_setprio 1
	v_mfma_f32_16x16x32_bf16 v[116:119], v[172:175], v[188:191], v[116:119]
	v_mfma_f32_16x16x32_bf16 v[112:115], v[180:183], v[188:191], v[112:115]
	v_mfma_f32_16x16x32_bf16 v[100:103], v[172:175], v[196:199], v[100:103]
	v_mfma_f32_16x16x32_bf16 v[96:99], v[180:183], v[196:199], v[96:99]
	v_mfma_f32_16x16x32_bf16 v[84:87], v[172:175], v[204:207], v[84:87]
	v_mfma_f32_16x16x32_bf16 v[80:83], v[180:183], v[204:207], v[80:83]
	v_mfma_f32_16x16x32_bf16 v[68:71], v[172:175], v[212:215], v[68:71]
	v_mfma_f32_16x16x32_bf16 v[64:67], v[180:183], v[212:215], v[64:67]
	v_mfma_f32_16x16x32_bf16 v[116:119], v[176:179], v[192:195], v[116:119]
	v_mfma_f32_16x16x32_bf16 v[112:115], v[184:187], v[192:195], v[112:115]
	v_mfma_f32_16x16x32_bf16 v[100:103], v[176:179], v[200:203], v[100:103]
	v_mfma_f32_16x16x32_bf16 v[96:99], v[184:187], v[200:203], v[96:99]
	v_mfma_f32_16x16x32_bf16 v[84:87], v[176:179], v[208:211], v[84:87]
	v_mfma_f32_16x16x32_bf16 v[80:83], v[184:187], v[208:211], v[80:83]
	v_mfma_f32_16x16x32_bf16 v[68:71], v[176:179], v[216:219], v[68:71]
	v_mfma_f32_16x16x32_bf16 v[64:67], v[184:187], v[216:219], v[64:67]
	s_setprio 0
	s_barrier
; #define PG8_STAGE(bufoff, gbase, voff) do { _Pragma("unroll") for (int _i = 0; _i < 2; ++_i) \
;         __builtin_amdgcn_global_load_lds((const unsigned*)((const char*)(gbase) + (voff)[_i]), (PG8_LAS unsigned*)(lds + (bufoff) + ldsw + _i * 8192), 16, 0, 0); } while (0)
; #define PG8_LDA(dst, b, h) do { _Pragma("unroll") for (int m = 0; m < 4; ++m) _Pragma("unroll") for (int k = 0; k < 2; ++k) dst[m][k] = *(const PG8_LAS bf16x8*)(lds + PG8_SA(b, h) + aoff + m * 2048 + k * 1024); } while (0)
; #define PG8_MMA(ai, bj, At, Bt) do { __builtin_amdgcn_s_setprio(1); _Pragma("unroll") for (int m = 0; m < 4; ++m) _Pragma("unroll") for (int n = 0; n < 2; ++n) _Pragma("unroll") for (int k = 0; k < 2; ++k) \
;         acc[ai][bj][m][n] = __builtin_amdgcn_mfma_f32_16x16x32_bf16(Bt[n][k], At[m][k], acc[ai][bj][m][n], 0, 0, 0); __builtin_amdgcn_s_setprio(0); } while (0)
; #define PG8_WAIT_V(n) asm volatile("s_waitcnt vmcnt(" #n ")" ::: "memory")
; #define PG8_WAIT_L(n) asm volatile("s_waitcnt lgkmcnt(" #n ")" ::: "memory")
; #define PG8_BAR __builtin_amdgcn_s_barrier()
; #define PG8_SCHED __builtin_amdgcn_sched_barrier(0)
; template <class Epi, class Sched, bool ALIGN_EPI = false, bool SP2 = false>
; __device__ __forceinline__ void gemm_phase(PG8_LAS unsigned char* lds, const Gemm g, const Sched& S, const Epi& E, int tid_in) {
;     ...
;         for (int t = 0; t < nt; t += 2) {
;     ...
;             PG8_LDA(At, 1, 1); PG8_STAGE(PG8_SB(1, 0), b3, voffB); PG8_STAGE(PG8_SB(1, 1), b3 + hstep, voffB); PG8_STAGE(PG8_SA(1, 0), a3, voffA);
;             PG8_WAIT_V(8); PG8_WAIT_L(0); PG8_BAR; PG8_MMA(1, 0, At, B0); PG8_MMA(1, 1, At, B1); PG8_BAR; PG8_SCHED;
	s_add_i32 s40, s85, s34
	v_lshl_add_u64 v[146:147], v[146:147], 0, s[52:53]
	s_mov_b32 m0, s40
	ds_read_b128 v[188:191], v151 offset:49152
	ds_read_b128 v[192:195], v151 offset:50176
	ds_read_b128 v[196:199], v151 offset:51200
	ds_read_b128 v[200:203], v151 offset:52224
	ds_read_b128 v[204:207], v151 offset:53248
	ds_read_b128 v[208:211], v151 offset:54272
	ds_read_b128 v[212:215], v151 offset:55296
	ds_read_b128 v[216:219], v151 offset:56320
	global_load_lds_dwordx4 v[146:147], off
	v_lshl_add_u64 v[146:147], v[164:165], 0, s[52:53]
	s_add_i32 m0, s40, 0x2000
	s_add_i32 s40, s90, s34
	global_load_lds_dwordx4 v[146:147], off
	v_lshl_add_u64 v[146:147], v[220:221], 0, s[52:53]
	s_mov_b32 m0, s40
	s_nop 0
	global_load_lds_dwordx4 v[146:147], off
	v_lshl_add_u64 v[146:147], v[222:223], 0, s[52:53]
	s_add_i32 m0, s40, 0x2000
	s_nop 0
	global_load_lds_dwordx4 v[146:147], off
	v_lshl_add_u64 v[146:147], v[224:225], 0, s[52:53]
	s_mov_b32 m0, s58
	s_nop 0
	global_load_lds_dwordx4 v[146:147], off
	v_lshl_add_u64 v[146:147], v[226:227], 0, s[52:53]
	s_mov_b32 m0, s66
	s_nop 0
	global_load_lds_dwordx4 v[146:147], off
	s_waitcnt vmcnt(8)
	s_waitcnt lgkmcnt(0)
	s_barrier
	s_setprio 1
	s_waitcnt lgkmcnt(0)
	v_mfma_f32_16x16x32_bf16 v[60:63], v[142:145], v[188:191], v[60:63]
	v_mfma_f32_16x16x32_bf16 v[56:59], v[156:159], v[188:191], v[56:59]
	v_mfma_f32_16x16x32_bf16 v[44:47], v[142:145], v[196:199], v[44:47]
	v_mfma_f32_16x16x32_bf16 v[40:43], v[156:159], v[196:199], v[40:43]
	v_mfma_f32_16x16x32_bf16 v[28:31], v[142:145], v[204:207], v[28:31]
	v_mfma_f32_16x16x32_bf16 v[24:27], v[156:159], v[204:207], v[24:27]
	v_mfma_f32_16x16x32_bf16 v[12:15], v[142:145], v[212:215], v[12:15]
	v_mfma_f32_16x16x32_bf16 v[8:11], v[156:159], v[212:215], v[8:11]
	v_mfma_f32_16x16x32_bf16 v[60:63], v[152:155], v[192:195], v[60:63]
	v_mfma_f32_16x16x32_bf16 v[56:59], v[160:163], v[192:195], v[56:59]
	v_mfma_f32_16x16x32_bf16 v[44:47], v[152:155], v[200:203], v[44:47]
	v_mfma_f32_16x16x32_bf16 v[40:43], v[160:163], v[200:203], v[40:43]
	v_mfma_f32_16x16x32_bf16 v[28:31], v[152:155], v[208:211], v[28:31]
	v_mfma_f32_16x16x32_bf16 v[24:27], v[160:163], v[208:211], v[24:27]
	v_mfma_f32_16x16x32_bf16 v[12:15], v[152:155], v[216:219], v[12:15]
	v_mfma_f32_16x16x32_bf16 v[8:11], v[160:163], v[216:219], v[8:11]
	s_setprio 0
	s_setprio 1
	v_mfma_f32_16x16x32_bf16 v[52:55], v[172:175], v[188:191], v[52:55]
	v_mfma_f32_16x16x32_bf16 v[48:51], v[180:183], v[188:191], v[48:51]
	v_mfma_f32_16x16x32_bf16 v[36:39], v[172:175], v[196:199], v[36:39]
	v_mfma_f32_16x16x32_bf16 v[32:35], v[180:183], v[196:199], v[32:35]
	v_mfma_f32_16x16x32_bf16 v[20:23], v[172:175], v[204:207], v[20:23]
	v_mfma_f32_16x16x32_bf16 v[16:19], v[180:183], v[204:207], v[16:19]
	v_mfma_f32_16x16x32_bf16 v[4:7], v[172:175], v[212:215], v[4:7]
	v_mfma_f32_16x16x32_bf16 v[0:3], v[180:183], v[212:215], v[0:3]
	v_mfma_f32_16x16x32_bf16 v[52:55], v[176:179], v[192:195], v[52:55]
	v_mfma_f32_16x16x32_bf16 v[48:51], v[184:187], v[192:195], v[48:51]
	v_mfma_f32_16x16x32_bf16 v[36:39], v[176:179], v[200:203], v[36:39]
	v_mfma_f32_16x16x32_bf16 v[32:35], v[184:187], v[200:203], v[32:35]
	v_mfma_f32_16x16x32_bf16 v[20:23], v[176:179], v[208:211], v[20:23]
	v_mfma_f32_16x16x32_bf16 v[16:19], v[184:187], v[208:211], v[16:19]
	v_mfma_f32_16x16x32_bf16 v[4:7], v[176:179], v[216:219], v[4:7]
	v_mfma_f32_16x16x32_bf16 v[0:3], v[184:187], v[216:219], v[0:3]
	s_add_u32 s38, s38, 0x100
	s_addc_u32 s39, s39, 0
	s_add_u32 s81, s81, 0x100
	s_addc_u32 s83, s83, 0
	s_cmp_ge_i32 s84, s70
	s_mov_b32 s40, s84
	s_setprio 0
	s_barrier
	s_cbranch_scc0 .LBB0_188

; #define PG8_STAGE(bufoff, gbase, voff) do { _Pragma("unroll") for (int _i = 0; _i < 2; ++_i) \
;         __builtin_amdgcn_global_load_lds((const unsigned*)((const char*)(gbase) + (voff)[_i]), (PG8_LAS unsigned*)(lds + (bufoff) + ldsw + _i * 8192), 16, 0, 0); } while (0)
; #define PG8_WAIT_V(n) asm volatile("s_waitcnt vmcnt(" #n ")" ::: "memory")
; #define PG8_BAR __builtin_amdgcn_s_barrier()
; template <class Epi, class Sched, bool ALIGN_EPI = false, bool SP2 = false>
; __device__ __forceinline__ void gemm_phase(PG8_LAS unsigned char* lds, const Gemm g, const Sched& S, const Epi& E, int tid_in) {
;     ...
;         PG8_STAGE(PG8_SB(0, 0), cB, voffB); PG8_STAGE(PG8_SB(0, 1), cB + hstep, voffB); PG8_STAGE(PG8_SA(0, 0), cA, voffA); PG8_STAGE(PG8_SA(0, 1), cA + hstep, voffA);
;         if (wr == 1) PG8_BAR;
;         PG8_WAIT_V(2); PG8_BAR;
;         PG8_STAGE(PG8_SB(1, 0), cB + kstep, voffB); PG8_STAGE(PG8_SA(1, 0), cA + kstep, voffA); PG8_STAGE(PG8_SB(1, 1), cB + hstep + kstep, voffB);
;         PG8_WAIT_V(6); PG8_BAR;
.LBB0_354:
	s_add_i32 m0, s34, 0x18000
	v_lshl_add_u64 v[0:1], v[0:1], 0, s[52:53]
	global_load_lds_dwordx4 v[0:1], off
	v_lshl_add_u64 v[0:1], v[2:3], 0, s[52:53]
	s_add_i32 m0, s34, 0x1a000
	s_add_i32 s71, s34, 0x8000
	global_load_lds_dwordx4 v[0:1], off
	v_lshl_add_u64 v[0:1], v[8:9], 0, s[52:53]
	s_mov_b32 m0, s71
	s_add_i32 s74, s34, 0xa000
	global_load_lds_dwordx4 v[0:1], off
	v_lshl_add_u64 v[0:1], v[10:11], 0, s[52:53]
	s_mov_b32 m0, s74
	v_bfe_u32 v148, v18, 4, 2
	global_load_lds_dwordx4 v[0:1], off
	s_add_i32 m0, s34, 0x1c000
	v_lshl_add_u64 v[0:1], v[4:5], 0, s[52:53]
	global_load_lds_dwordx4 v[0:1], off
	v_lshl_add_u64 v[0:1], v[6:7], 0, s[52:53]
	s_add_i32 m0, s34, 0x1e000
	s_lshr_b32 s3, s3, 26
	global_load_lds_dwordx4 v[0:1], off
	s_waitcnt vmcnt(8)
	s_barrier
	v_and_b32_e32 v149, 15, v18
	s_add_i32 s3, s2, s3
	v_lshlrev_b32_e32 v19, 4, v148
	v_lshlrev_b32_e32 v18, 2, v18
	s_ashr_i32 s58, s3, 6
	v_lshl_or_b32 v19, v149, 6, v19
	s_lshl_b32 s3, s4, 13
	v_and_b32_e32 v18, 32, v18
	v_bitop3_b32 v20, v19, s3, v18 bitop3:0xde
	s_lshl_b32 s3, s5, 5
	s_and_b32 s70, s3, 0x60
	s_lshl_b32 s66, s4, 6
	s_lshl_b32 s3, s70, 7
	s_cmp_gt_i32 s2, 63
	s_cselect_b64 s[40:41], -1, 0
	s_add_i32 s77, s58, -2
	s_cmpk_lt_u32 s13, 0x100
	s_cselect_b64 s[42:43], -1, 0
	s_lshl_b32 s79, s11, 3
	s_abs_i32 s81, s79
	v_cvt_f32_u32_e32 v0, s81
	v_bitop3_b32 v150, v19, s3, v18 bitop3:0xde
	s_sub_i32 s2, 0, s81
	v_mov_b32_e32 v1, v137
	v_rcp_iflag_f32_e32 v0, v0
	s_waitcnt vmcnt(6)
	s_ashr_i32 s78, s18, 31
	s_ashr_i32 s13, s12, 31
	v_mul_f32_e32 v0, 0x4f7ffffe, v0
	v_cvt_u32_f32_e32 v0, v0
	s_bfe_i32 s80, s11, 0x1001c
	s_mov_b32 s30, 0
	v_add_u32_e32 v151, 0, v20
	v_readfirstlane_b32 s3, v0
	v_add_u32_e32 v0, v14, v12
	v_add_lshl_u32 v0, v0, v13, 1
	s_mul_i32 s2, s2, s3
	v_lshl_add_u64 v[134:135], s[26:27], 0, v[0:1]
	v_add_u32_e32 v0, v17, v15
	s_mul_hi_u32 s2, s3, s2
	v_add_lshl_u32 v0, v0, v16, 1
	s_add_i32 s83, s3, s2
	v_lshl_add_u64 v[140:141], s[26:27], 0, v[0:1]
	s_mov_b32 s69, 0x10000
	s_barrier
	s_branch .LBB0_357

; #define PG8_STAGE(bufoff, gbase, voff) do { _Pragma("unroll") for (int _i = 0; _i < 2; ++_i) \
;         __builtin_amdgcn_global_load_lds((const unsigned*)((const char*)(gbase) + (voff)[_i]), (PG8_LAS unsigned*)(lds + (bufoff) + ldsw + _i * 8192), 16, 0, 0); } while (0)
; #define PG8_LDA(dst, b, h) do { _Pragma("unroll") for (int m = 0; m < 4; ++m) _Pragma("unroll") for (int k = 0; k < 2; ++k) dst[m][k] = *(const PG8_LAS bf16x8*)(lds + PG8_SA(b, h) + aoff + m * 2048 + k * 1024); } while (0)
; #define PG8_LDB(dst, b, h) do { _Pragma("unroll") for (int n = 0; n < 2; ++n) _Pragma("unroll") for (int k = 0; k < 2; ++k) dst[n][k] = *(const PG8_LAS bf16x8*)(lds + PG8_SB(b, h) + boff + n * 2048 + k * 1024); } while (0)
; #define PG8_MMA(ai, bj, At, Bt) do { __builtin_amdgcn_s_setprio(1); _Pragma("unroll") for (int m = 0; m < 4; ++m) _Pragma("unroll") for (int n = 0; n < 2; ++n) _Pragma("unroll") for (int k = 0; k < 2; ++k) \
;         acc[ai][bj][m][n] = __builtin_amdgcn_mfma_f32_16x16x32_bf16(Bt[n][k], At[m][k], acc[ai][bj][m][n], 0, 0, 0); __builtin_amdgcn_s_setprio(0); } while (0)
; #define PG8_WAIT_V(n) asm volatile("s_waitcnt vmcnt(" #n ")" ::: "memory")
; #define PG8_WAIT_L(n) asm volatile("s_waitcnt lgkmcnt(" #n ")" ::: "memory")
; #define PG8_BAR __builtin_amdgcn_s_barrier()
; #define PG8_SCHED __builtin_amdgcn_sched_barrier(0)
; template <class Epi, class Sched, bool ALIGN_EPI = false, bool SP2 = false>
; __device__ __forceinline__ void gemm_phase(PG8_LAS unsigned char* lds, const Gemm g, const Sched& S, const Epi& E, int tid_in) {
;     ...
;             PG8_LDB(B0, 0, 0); PG8_LDB(B1, 0, 1); PG8_SCHED; PG8_LDA(At, 0, 0); PG8_STAGE(PG8_SA(1, 1), a1 + hstep, voffA);
;             PG8_WAIT_V(8); PG8_WAIT_L(0); PG8_BAR; PG8_MMA(0, 0, At, B0); PG8_MMA(0, 1, At, B1); PG8_BAR; PG8_SCHED;
;             PG8_LDA(At, 0, 1); PG8_STAGE(PG8_SB(0, 0), b2, voffB); PG8_STAGE(PG8_SB(0, 1), b2 + hstep, voffB); PG8_STAGE(PG8_SA(0, 0), a2, voffA);
;             PG8_WAIT_V(8); PG8_WAIT_L(0); PG8_BAR; PG8_MMA(1, 0, At, B0); PG8_MMA(1, 1, At, B1); PG8_BAR; PG8_SCHED;
.LBB0_365:
	s_add_i32 s11, s6, 2
	s_add_u32 s33, s4, 0x80
	s_addc_u32 s7, s5, 0
	s_add_i32 s90, 0, 0x10000
	s_cmp_eq_u32 s77, s6
	s_cselect_b32 s7, s55, s7
	s_cselect_b32 s6, s54, s33
	v_add_u32_e32 v139, s90, v150
	s_cselect_b32 s45, s89, s9
	s_cselect_b32 s44, s88, s8
	s_add_i32 s33, 0, 0x14000
	ds_read_b128 v[142:145], v139
	ds_read_b128 v[152:155], v139 offset:1024
	ds_read_b128 v[156:159], v139 offset:2048
	ds_read_b128 v[160:163], v139 offset:3072
	v_add_u32_e32 v139, s33, v150
	ds_read_b128 v[172:175], v139
	ds_read_b128 v[176:179], v139 offset:1024
	ds_read_b128 v[180:183], v139 offset:2048
	ds_read_b128 v[184:187], v139 offset:3072
	v_lshl_add_u64 v[146:147], s[4:5], 0, v[134:135]
	s_add_i32 m0, s34, 0xc000
	ds_read_b128 v[188:191], v151
	ds_read_b128 v[192:195], v151 offset:1024
	ds_read_b128 v[196:199], v151 offset:2048
	ds_read_b128 v[200:203], v151 offset:3072
	ds_read_b128 v[204:207], v151 offset:4096
	ds_read_b128 v[208:211], v151 offset:5120
	ds_read_b128 v[212:215], v151 offset:6144
	ds_read_b128 v[216:219], v151 offset:7168
	global_load_lds_dwordx4 v[146:147], off
	v_lshl_add_u64 v[146:147], s[4:5], 0, v[140:141]
	s_add_i32 m0, s34, 0xe000
	s_nop 0
	global_load_lds_dwordx4 v[146:147], off
	s_waitcnt vmcnt(8)
	s_waitcnt lgkmcnt(0)
	s_barrier
	s_setprio 1
	s_waitcnt lgkmcnt(0)
	v_mfma_f32_16x16x32_bf16 v[120:123], v[142:145], v[188:191], v[120:123]
	v_mfma_f32_16x16x32_bf16 v[124:127], v[156:159], v[188:191], v[124:127]
	v_mfma_f32_16x16x32_bf16 v[108:111], v[142:145], v[196:199], v[108:111]
	v_mfma_f32_16x16x32_bf16 v[104:107], v[156:159], v[196:199], v[104:107]
	v_mfma_f32_16x16x32_bf16 v[92:95], v[142:145], v[204:207], v[92:95]
	v_mfma_f32_16x16x32_bf16 v[88:91], v[156:159], v[204:207], v[88:91]
	v_mfma_f32_16x16x32_bf16 v[76:79], v[142:145], v[212:215], v[76:79]
	v_mfma_f32_16x16x32_bf16 v[72:75], v[156:159], v[212:215], v[72:75]
	v_mfma_f32_16x16x32_bf16 v[120:123], v[152:155], v[192:195], v[120:123]
	v_mfma_f32_16x16x32_bf16 v[124:127], v[160:163], v[192:195], v[124:127]
	v_mfma_f32_16x16x32_bf16 v[108:111], v[152:155], v[200:203], v[108:111]
	v_mfma_f32_16x16x32_bf16 v[104:107], v[160:163], v[200:203], v[104:107]
	v_mfma_f32_16x16x32_bf16 v[92:95], v[152:155], v[208:211], v[92:95]
	v_mfma_f32_16x16x32_bf16 v[88:91], v[160:163], v[208:211], v[88:91]
	v_mfma_f32_16x16x32_bf16 v[76:79], v[152:155], v[216:219], v[76:79]
	v_mfma_f32_16x16x32_bf16 v[72:75], v[160:163], v[216:219], v[72:75]
	s_setprio 0
	s_setprio 1
	v_mfma_f32_16x16x32_bf16 v[116:119], v[172:175], v[188:191], v[116:119]
	v_mfma_f32_16x16x32_bf16 v[112:115], v[180:183], v[188:191], v[112:115]
	v_mfma_f32_16x16x32_bf16 v[100:103], v[172:175], v[196:199], v[100:103]
	v_mfma_f32_16x16x32_bf16 v[96:99], v[180:183], v[196:199], v[96:99]
	v_mfma_f32_16x16x32_bf16 v[84:87], v[172:175], v[204:207], v[84:87]
	v_mfma_f32_16x16x32_bf16 v[80:83], v[180:183], v[204:207], v[80:83]
	v_mfma_f32_16x16x32_bf16 v[68:71], v[172:175], v[212:215], v[68:71]
	v_mfma_f32_16x16x32_bf16 v[64:67], v[180:183], v[212:215], v[64:67]
	v_mfma_f32_16x16x32_bf16 v[116:119], v[176:179], v[192:195], v[116:119]
	v_mfma_f32_16x16x32_bf16 v[112:115], v[184:187], v[192:195], v[112:115]
	v_mfma_f32_16x16x32_bf16 v[100:103], v[176:179], v[200:203], v[100:103]
	v_mfma_f32_16x16x32_bf16 v[96:99], v[184:187], v[200:203], v[96:99]
	v_mfma_f32_16x16x32_bf16 v[84:87], v[176:179], v[208:211], v[84:87]
	v_mfma_f32_16x16x32_bf16 v[80:83], v[184:187], v[208:211], v[80:83]
	v_mfma_f32_16x16x32_bf16 v[68:71], v[176:179], v[216:219], v[68:71]
	v_mfma_f32_16x16x32_bf16 v[64:67], v[184:187], v[216:219], v[64:67]
	s_setprio 0
	s_barrier
	s_add_i32 s90, s90, s29
	v_lshl_add_u64 v[146:147], s[44:45], 0, v[136:137]
	s_mov_b32 m0, s90
	ds_read_b128 v[188:191], v151 offset:16384
	ds_read_b128 v[192:195], v151 offset:17408
	ds_read_b128 v[196:199], v151 offset:18432
	ds_read_b128 v[200:203], v151 offset:19456
	ds_read_b128 v[204:207], v151 offset:20480
	ds_read_b128 v[208:211], v151 offset:21504
	ds_read_b128 v[212:215], v151 offset:22528
	ds_read_b128 v[216:219], v151 offset:23552
	global_load_lds_dwordx4 v[146:147], off
	s_add_i32 m0, s90, 0x2000
	v_lshl_add_u64 v[164:165], s[44:45], 0, v[132:133]
	s_add_u32 s44, s44, s26
	s_addc_u32 s45, s45, s27
	s_add_i32 s33, s33, s29
	global_load_lds_dwordx4 v[164:165], off
	v_lshl_add_u64 v[220:221], s[44:45], 0, v[136:137]
	s_mov_b32 m0, s33
	v_lshl_add_u64 v[222:223], s[44:45], 0, v[132:133]
	global_load_lds_dwordx4 v[220:221], off
	s_add_i32 m0, s33, 0x2000
	v_lshl_add_u64 v[224:225], s[6:7], 0, v[128:129]
	global_load_lds_dwordx4 v[222:223], off
	s_mov_b32 m0, s34
	v_lshl_add_u64 v[226:227], s[6:7], 0, v[130:131]
	global_load_lds_dwordx4 v[224:225], off
	s_mov_b32 m0, s46
	s_nop 0
	global_load_lds_dwordx4 v[226:227], off
	s_waitcnt vmcnt(8)
	s_waitcnt lgkmcnt(0)
	s_barrier
; #define PG8_STAGE(bufoff, gbase, voff) do { _Pragma("unroll") for (int _i = 0; _i < 2; ++_i) \
;         __builtin_amdgcn_global_load_lds((const unsigned*)((const char*)(gbase) + (voff)[_i]), (PG8_LAS unsigned*)(lds + (bufoff) + ldsw + _i * 8192), 16, 0, 0); } while (0)
; #define PG8_LDA(dst, b, h) do { _Pragma("unroll") for (int m = 0; m < 4; ++m) _Pragma("unroll") for (int k = 0; k < 2; ++k) dst[m][k] = *(const PG8_LAS bf16x8*)(lds + PG8_SA(b, h) + aoff + m * 2048 + k * 1024); } while (0)
; #define PG8_LDB(dst, b, h) do { _Pragma("unroll") for (int n = 0; n < 2; ++n) _Pragma("unroll") for (int k = 0; k < 2; ++k) dst[n][k] = *(const PG8_LAS bf16x8*)(lds + PG8_SB(b, h) + boff + n * 2048 + k * 1024); } while (0)
; #define PG8_MMA(ai, bj, At, Bt) do { __builtin_amdgcn_s_setprio(1); _Pragma("unroll") for (int m = 0; m < 4; ++m) _Pragma("unroll") for (int n = 0; n < 2; ++n) _Pragma("unroll") for (int k = 0; k < 2; ++k) \
;         acc[ai][bj][m][n] = __builtin_amdgcn_mfma_f32_16x16x32_bf16(Bt[n][k], At[m][k], acc[ai][bj][m][n], 0, 0, 0); __builtin_amdgcn_s_setprio(0); } while (0)
; #define PG8_WAIT_V(n) asm volatile("s_waitcnt vmcnt(" #n ")" ::: "memory")
; #define PG8_WAIT_L(n) asm volatile("s_waitcnt lgkmcnt(" #n ")" ::: "memory")
; #define PG8_BAR __builtin_amdgcn_s_barrier()
; #define PG8_SCHED __builtin_amdgcn_sched_barrier(0)
; template <class Epi, class Sched, bool ALIGN_EPI = false, bool SP2 = false>
; __device__ __forceinline__ void gemm_phase(PG8_LAS unsigned char* lds, const Gemm g, const Sched& S, const Epi& E, int tid_in) {
;     ...
;             PG8_WAIT_V(8); PG8_WAIT_L(0); PG8_BAR; PG8_MMA(1, 0, At, B0); PG8_MMA(1, 1, At, B1); PG8_BAR; PG8_SCHED;
;             PG8_LDB(B0, 1, 0); PG8_LDB(B1, 1, 1); PG8_SCHED; PG8_LDA(At, 1, 0); PG8_STAGE(PG8_SA(0, 1), a2 + hstep, voffA);
;             PG8_WAIT_V(8); PG8_WAIT_L(0); PG8_BAR; PG8_MMA(0, 0, At, B0); PG8_MMA(0, 1, At, B1); PG8_BAR; PG8_SCHED;
	s_setprio 1
	s_waitcnt lgkmcnt(0)
	v_mfma_f32_16x16x32_bf16 v[60:63], v[142:145], v[188:191], v[60:63]
	v_mfma_f32_16x16x32_bf16 v[56:59], v[156:159], v[188:191], v[56:59]
	v_mfma_f32_16x16x32_bf16 v[44:47], v[142:145], v[196:199], v[44:47]
	v_mfma_f32_16x16x32_bf16 v[40:43], v[156:159], v[196:199], v[40:43]
	v_mfma_f32_16x16x32_bf16 v[28:31], v[142:145], v[204:207], v[28:31]
	v_mfma_f32_16x16x32_bf16 v[24:27], v[156:159], v[204:207], v[24:27]
	v_mfma_f32_16x16x32_bf16 v[12:15], v[142:145], v[212:215], v[12:15]
	v_mfma_f32_16x16x32_bf16 v[8:11], v[156:159], v[212:215], v[8:11]
	v_mfma_f32_16x16x32_bf16 v[60:63], v[152:155], v[192:195], v[60:63]
	v_mfma_f32_16x16x32_bf16 v[56:59], v[160:163], v[192:195], v[56:59]
	v_mfma_f32_16x16x32_bf16 v[44:47], v[152:155], v[200:203], v[44:47]
	v_mfma_f32_16x16x32_bf16 v[40:43], v[160:163], v[200:203], v[40:43]
	v_mfma_f32_16x16x32_bf16 v[28:31], v[152:155], v[208:211], v[28:31]
	v_mfma_f32_16x16x32_bf16 v[24:27], v[160:163], v[208:211], v[24:27]
	v_mfma_f32_16x16x32_bf16 v[12:15], v[152:155], v[216:219], v[12:15]
	v_mfma_f32_16x16x32_bf16 v[8:11], v[160:163], v[216:219], v[8:11]
	s_setprio 0
	s_setprio 1
	v_mfma_f32_16x16x32_bf16 v[52:55], v[172:175], v[188:191], v[52:55]
	v_mfma_f32_16x16x32_bf16 v[48:51], v[180:183], v[188:191], v[48:51]
	v_mfma_f32_16x16x32_bf16 v[36:39], v[172:175], v[196:199], v[36:39]
	v_mfma_f32_16x16x32_bf16 v[32:35], v[180:183], v[196:199], v[32:35]
	v_mfma_f32_16x16x32_bf16 v[20:23], v[172:175], v[204:207], v[20:23]
	v_mfma_f32_16x16x32_bf16 v[16:19], v[180:183], v[204:207], v[16:19]
	v_mfma_f32_16x16x32_bf16 v[4:7], v[172:175], v[212:215], v[4:7]
	v_mfma_f32_16x16x32_bf16 v[0:3], v[180:183], v[212:215], v[0:3]
	v_mfma_f32_16x16x32_bf16 v[52:55], v[176:179], v[192:195], v[52:55]
	v_mfma_f32_16x16x32_bf16 v[48:51], v[184:187], v[192:195], v[48:51]
	v_mfma_f32_16x16x32_bf16 v[36:39], v[176:179], v[200:203], v[36:39]
	v_mfma_f32_16x16x32_bf16 v[32:35], v[184:187], v[200:203], v[32:35]
	v_mfma_f32_16x16x32_bf16 v[20:23], v[176:179], v[208:211], v[20:23]
	v_mfma_f32_16x16x32_bf16 v[16:19], v[184:187], v[208:211], v[16:19]
	v_mfma_f32_16x16x32_bf16 v[4:7], v[176:179], v[216:219], v[4:7]
	v_mfma_f32_16x16x32_bf16 v[0:3], v[184:187], v[216:219], v[0:3]
	s_setprio 0
	s_barrier
	s_add_i32 s33, 0, 0x18000
	v_add_u32_e32 v139, s33, v150
	s_add_i32 s44, 0, 0x1c000
	ds_read_b128 v[142:145], v139
	ds_read_b128 v[152:155], v139 offset:1024
	ds_read_b128 v[156:159], v139 offset:2048
	ds_read_b128 v[160:163], v139 offset:3072
	v_add_u32_e32 v139, s44, v150
	ds_read_b128 v[172:175], v139
	ds_read_b128 v[176:179], v139 offset:1024
	ds_read_b128 v[180:183], v139 offset:2048
	ds_read_b128 v[184:187], v139 offset:3072
	s_add_u32 s6, s6, s26
	s_addc_u32 s7, s7, s27
	s_mov_b32 m0, s48
	v_lshl_add_u64 v[228:229], s[6:7], 0, v[128:129]
	ds_read_b128 v[188:191], v151 offset:32768
	ds_read_b128 v[192:195], v151 offset:33792
	ds_read_b128 v[196:199], v151 offset:34816
	ds_read_b128 v[200:203], v151 offset:35840
	ds_read_b128 v[204:207], v151 offset:36864
	ds_read_b128 v[208:211], v151 offset:37888
	ds_read_b128 v[212:215], v151 offset:38912
	ds_read_b128 v[216:219], v151 offset:39936
	global_load_lds_dwordx4 v[228:229], off
	v_lshl_add_u64 v[228:229], s[6:7], 0, v[130:131]
	s_mov_b32 m0, s49
	s_nop 0
	global_load_lds_dwordx4 v[228:229], off
	s_waitcnt vmcnt(8)
	s_waitcnt lgkmcnt(0)
	s_barrier
	s_setprio 1
	s_waitcnt lgkmcnt(0)
	v_mfma_f32_16x16x32_bf16 v[120:123], v[142:145], v[188:191], v[120:123]
	v_mfma_f32_16x16x32_bf16 v[124:127], v[156:159], v[188:191], v[124:127]
	v_mfma_f32_16x16x32_bf16 v[108:111], v[142:145], v[196:199], v[108:111]
	v_mfma_f32_16x16x32_bf16 v[104:107], v[156:159], v[196:199], v[104:107]
	v_mfma_f32_16x16x32_bf16 v[92:95], v[142:145], v[204:207], v[92:95]
	v_mfma_f32_16x16x32_bf16 v[88:91], v[156:159], v[204:207], v[88:91]
	v_mfma_f32_16x16x32_bf16 v[76:79], v[142:145], v[212:215], v[76:79]
	v_mfma_f32_16x16x32_bf16 v[72:75], v[156:159], v[212:215], v[72:75]
	v_mfma_f32_16x16x32_bf16 v[120:123], v[152:155], v[192:195], v[120:123]
	v_mfma_f32_16x16x32_bf16 v[124:127], v[160:163], v[192:195], v[124:127]
	v_mfma_f32_16x16x32_bf16 v[108:111], v[152:155], v[200:203], v[108:111]
	v_mfma_f32_16x16x32_bf16 v[104:107], v[160:163], v[200:203], v[104:107]
	v_mfma_f32_16x16x32_bf16 v[92:95], v[152:155], v[208:211], v[92:95]
	v_mfma_f32_16x16x32_bf16 v[88:91], v[160:163], v[208:211], v[88:91]
	v_mfma_f32_16x16x32_bf16 v[76:79], v[152:155], v[216:219], v[76:79]
	v_mfma_f32_16x16x32_bf16 v[72:75], v[160:163], v[216:219], v[72:75]
	s_setprio 0
	s_setprio 1
	v_mfma_f32_16x16x32_bf16 v[116:119], v[172:175], v[188:191], v[116:119]
	v_mfma_f32_16x16x32_bf16 v[112:115], v[180:183], v[188:191], v[112:115]
	v_mfma_f32_16x16x32_bf16 v[100:103], v[172:175], v[196:199], v[100:103]
	v_mfma_f32_16x16x32_bf16 v[96:99], v[180:183], v[196:199], v[96:99]
	v_mfma_f32_16x16x32_bf16 v[84:87], v[172:175], v[204:207], v[84:87]
	v_mfma_f32_16x16x32_bf16 v[80:83], v[180:183], v[204:207], v[80:83]
	v_mfma_f32_16x16x32_bf16 v[68:71], v[172:175], v[212:215], v[68:71]
	v_mfma_f32_16x16x32_bf16 v[64:67], v[180:183], v[212:215], v[64:67]
	v_mfma_f32_16x16x32_bf16 v[116:119], v[176:179], v[192:195], v[116:119]
	v_mfma_f32_16x16x32_bf16 v[112:115], v[184:187], v[192:195], v[112:115]
	v_mfma_f32_16x16x32_bf16 v[100:103], v[176:179], v[200:203], v[100:103]
	v_mfma_f32_16x16x32_bf16 v[96:99], v[184:187], v[200:203], v[96:99]
	v_mfma_f32_16x16x32_bf16 v[84:87], v[176:179], v[208:211], v[84:87]
	v_mfma_f32_16x16x32_bf16 v[80:83], v[184:187], v[208:211], v[80:83]
	v_mfma_f32_16x16x32_bf16 v[68:71], v[176:179], v[216:219], v[68:71]
	v_mfma_f32_16x16x32_bf16 v[64:67], v[184:187], v[216:219], v[64:67]
	s_setprio 0
	s_barrier
; #define PG8_STAGE(bufoff, gbase, voff) do { _Pragma("unroll") for (int _i = 0; _i < 2; ++_i) \
;         __builtin_amdgcn_global_load_lds((const unsigned*)((const char*)(gbase) + (voff)[_i]), (PG8_LAS unsigned*)(lds + (bufoff) + ldsw + _i * 8192), 16, 0, 0); } while (0)
; #define PG8_LDA(dst, b, h) do { _Pragma("unroll") for (int m = 0; m < 4; ++m) _Pragma("unroll") for (int k = 0; k < 2; ++k) dst[m][k] = *(const PG8_LAS bf16x8*)(lds + PG8_SA(b, h) + aoff + m * 2048 + k * 1024); } while (0)
; #define PG8_MMA(ai, bj, At, Bt) do { __builtin_amdgcn_s_setprio(1); _Pragma("unroll") for (int m = 0; m < 4; ++m) _Pragma("unroll") for (int n = 0; n < 2; ++n) _Pragma("unroll") for (int k = 0; k < 2; ++k) \
;         acc[ai][bj][m][n] = __builtin_amdgcn_mfma_f32_16x16x32_bf16(Bt[n][k], At[m][k], acc[ai][bj][m][n], 0, 0, 0); __builtin_amdgcn_s_setprio(0); } while (0)
; #define PG8_WAIT_V(n) asm volatile("s_waitcnt vmcnt(" #n ")" ::: "memory")
; #define PG8_WAIT_L(n) asm volatile("s_waitcnt lgkmcnt(" #n ")" ::: "memory")
; #define PG8_BAR __builtin_amdgcn_s_barrier()
; #define PG8_SCHED __builtin_amdgcn_sched_barrier(0)
; template <class Epi, class Sched, bool ALIGN_EPI = false, bool SP2 = false>
; __device__ __forceinline__ void gemm_phase(PG8_LAS unsigned char* lds, const Gemm g, const Sched& S, const Epi& E, int tid_in) {
;     ...
;         for (int t = 0; t < nt; t += 2) {
;     ...
;             PG8_LDA(At, 1, 1); PG8_STAGE(PG8_SB(1, 0), b3, voffB); PG8_STAGE(PG8_SB(1, 1), b3 + hstep, voffB); PG8_STAGE(PG8_SA(1, 0), a3, voffA);
;             PG8_WAIT_V(8); PG8_WAIT_L(0); PG8_BAR; PG8_MMA(1, 0, At, B0); PG8_MMA(1, 1, At, B1); PG8_BAR; PG8_SCHED;
	s_add_i32 s6, s33, s29
	v_lshl_add_u64 v[146:147], v[146:147], 0, s[52:53]
	s_mov_b32 m0, s6
	ds_read_b128 v[188:191], v151 offset:49152
	ds_read_b128 v[192:195], v151 offset:50176
	ds_read_b128 v[196:199], v151 offset:51200
	ds_read_b128 v[200:203], v151 offset:52224
	ds_read_b128 v[204:207], v151 offset:53248
	ds_read_b128 v[208:211], v151 offset:54272
	ds_read_b128 v[212:215], v151 offset:55296
	ds_read_b128 v[216:219], v151 offset:56320
	global_load_lds_dwordx4 v[146:147], off
	v_lshl_add_u64 v[146:147], v[164:165], 0, s[52:53]
	s_add_i32 m0, s6, 0x2000
	s_add_i32 s6, s44, s29
	global_load_lds_dwordx4 v[146:147], off
	v_lshl_add_u64 v[146:147], v[220:221], 0, s[52:53]
	s_mov_b32 m0, s6
	s_nop 0
	global_load_lds_dwordx4 v[146:147], off
	v_lshl_add_u64 v[146:147], v[222:223], 0, s[52:53]
	s_add_i32 m0, s6, 0x2000
	s_nop 0
	global_load_lds_dwordx4 v[146:147], off
	v_lshl_add_u64 v[146:147], v[224:225], 0, s[52:53]
	s_mov_b32 m0, s71
	s_nop 0
	global_load_lds_dwordx4 v[146:147], off
	v_lshl_add_u64 v[146:147], v[226:227], 0, s[52:53]
	s_mov_b32 m0, s74
	s_nop 0
	global_load_lds_dwordx4 v[146:147], off
	s_waitcnt vmcnt(8)
	s_waitcnt lgkmcnt(0)
	s_barrier
	s_setprio 1
	s_waitcnt lgkmcnt(0)
	v_mfma_f32_16x16x32_bf16 v[60:63], v[142:145], v[188:191], v[60:63]
	v_mfma_f32_16x16x32_bf16 v[56:59], v[156:159], v[188:191], v[56:59]
	v_mfma_f32_16x16x32_bf16 v[44:47], v[142:145], v[196:199], v[44:47]
	v_mfma_f32_16x16x32_bf16 v[40:43], v[156:159], v[196:199], v[40:43]
	v_mfma_f32_16x16x32_bf16 v[28:31], v[142:145], v[204:207], v[28:31]
	v_mfma_f32_16x16x32_bf16 v[24:27], v[156:159], v[204:207], v[24:27]
	v_mfma_f32_16x16x32_bf16 v[12:15], v[142:145], v[212:215], v[12:15]
	v_mfma_f32_16x16x32_bf16 v[8:11], v[156:159], v[212:215], v[8:11]
	v_mfma_f32_16x16x32_bf16 v[60:63], v[152:155], v[192:195], v[60:63]
	v_mfma_f32_16x16x32_bf16 v[56:59], v[160:163], v[192:195], v[56:59]
	v_mfma_f32_16x16x32_bf16 v[44:47], v[152:155], v[200:203], v[44:47]
	v_mfma_f32_16x16x32_bf16 v[40:43], v[160:163], v[200:203], v[40:43]
	v_mfma_f32_16x16x32_bf16 v[28:31], v[152:155], v[208:211], v[28:31]
	v_mfma_f32_16x16x32_bf16 v[24:27], v[160:163], v[208:211], v[24:27]
	v_mfma_f32_16x16x32_bf16 v[12:15], v[152:155], v[216:219], v[12:15]
	v_mfma_f32_16x16x32_bf16 v[8:11], v[160:163], v[216:219], v[8:11]
	s_setprio 0
	s_setprio 1
	v_mfma_f32_16x16x32_bf16 v[52:55], v[172:175], v[188:191], v[52:55]
	v_mfma_f32_16x16x32_bf16 v[48:51], v[180:183], v[188:191], v[48:51]
	v_mfma_f32_16x16x32_bf16 v[36:39], v[172:175], v[196:199], v[36:39]
	v_mfma_f32_16x16x32_bf16 v[32:35], v[180:183], v[196:199], v[32:35]
	v_mfma_f32_16x16x32_bf16 v[20:23], v[172:175], v[204:207], v[20:23]
	v_mfma_f32_16x16x32_bf16 v[16:19], v[180:183], v[204:207], v[16:19]
	v_mfma_f32_16x16x32_bf16 v[4:7], v[172:175], v[212:215], v[4:7]
	v_mfma_f32_16x16x32_bf16 v[0:3], v[180:183], v[212:215], v[0:3]
	v_mfma_f32_16x16x32_bf16 v[52:55], v[176:179], v[192:195], v[52:55]
	v_mfma_f32_16x16x32_bf16 v[48:51], v[184:187], v[192:195], v[48:51]
	v_mfma_f32_16x16x32_bf16 v[36:39], v[176:179], v[200:203], v[36:39]
	v_mfma_f32_16x16x32_bf16 v[32:35], v[184:187], v[200:203], v[32:35]
	v_mfma_f32_16x16x32_bf16 v[20:23], v[176:179], v[208:211], v[20:23]
	v_mfma_f32_16x16x32_bf16 v[16:19], v[184:187], v[208:211], v[16:19]
	v_mfma_f32_16x16x32_bf16 v[4:7], v[176:179], v[216:219], v[4:7]
	v_mfma_f32_16x16x32_bf16 v[0:3], v[184:187], v[216:219], v[0:3]
	s_add_u32 s4, s4, 0x100
	s_addc_u32 s5, s5, 0
	s_add_u32 s8, s8, 0x100
	s_addc_u32 s9, s9, 0
	s_cmp_ge_i32 s11, s58
	s_mov_b32 s6, s11
	s_setprio 0
	s_barrier
	s_cbranch_scc0 .LBB0_365

; #define PG8_STAGE(bufoff, gbase, voff) do { _Pragma("unroll") for (int _i = 0; _i < 2; ++_i) \
;         __builtin_amdgcn_global_load_lds((const unsigned*)((const char*)(gbase) + (voff)[_i]), (PG8_LAS unsigned*)(lds + (bufoff) + ldsw + _i * 8192), 16, 0, 0); } while (0)
; #define PG8_WAIT_V(n) asm volatile("s_waitcnt vmcnt(" #n ")" ::: "memory")
; #define PG8_BAR __builtin_amdgcn_s_barrier()
; template <class Epi, class Sched, bool ALIGN_EPI = false, bool SP2 = false>
; __device__ __forceinline__ void gemm_phase(PG8_LAS unsigned char* lds, const Gemm g, const Sched& S, const Epi& E, int tid_in) {
;     ...
;         PG8_STAGE(PG8_SB(0, 0), cB, voffB); PG8_STAGE(PG8_SB(0, 1), cB + hstep, voffB); PG8_STAGE(PG8_SA(0, 0), cA, voffA); PG8_STAGE(PG8_SA(0, 1), cA + hstep, voffA);
;         if (wr == 1) PG8_BAR;
;         PG8_WAIT_V(2); PG8_BAR;
;         PG8_STAGE(PG8_SB(1, 0), cB + kstep, voffB); PG8_STAGE(PG8_SA(1, 0), cA + kstep, voffA); PG8_STAGE(PG8_SB(1, 1), cB + hstep + kstep, voffB);
;         PG8_WAIT_V(6); PG8_BAR;
.LBB0_980:
	s_lshr_b32 s3, s3, 26
	s_add_i32 m0, s58, 0x18000
	v_lshl_add_u64 v[0:1], v[0:1], 0, s[52:53]
	s_add_i32 s3, s2, s3
	global_load_lds_dwordx4 v[0:1], off
	v_lshl_add_u64 v[0:1], v[2:3], 0, s[52:53]
	s_add_i32 m0, s58, 0x1a000
	s_add_i32 s46, s58, 0x8000
	s_ashr_i32 s48, s3, 6
	s_lshl_b32 s83, s19, 6
	s_lshl_b32 s3, s19, 13
	global_load_lds_dwordx4 v[0:1], off
	v_lshl_add_u64 v[0:1], v[8:9], 0, s[52:53]
	s_mov_b32 m0, s46
	s_add_i32 s19, s58, 0xa000
	global_load_lds_dwordx4 v[0:1], off
	v_lshl_add_u64 v[0:1], v[10:11], 0, s[52:53]
	s_mov_b32 m0, s19
	v_bfe_u32 v171, v18, 4, 2
	global_load_lds_dwordx4 v[0:1], off
	s_add_i32 m0, s58, 0x1c000
	v_lshl_add_u64 v[0:1], v[4:5], 0, s[52:53]
	global_load_lds_dwordx4 v[0:1], off
	v_lshl_add_u64 v[0:1], v[6:7], 0, s[52:53]
	s_add_i32 m0, s58, 0x1e000
	v_and_b32_e32 v172, 15, v18
	global_load_lds_dwordx4 v[0:1], off
	s_waitcnt vmcnt(8)
	s_barrier
	v_lshlrev_b32_e32 v19, 4, v171
	v_lshlrev_b32_e32 v18, 2, v18
	v_lshl_or_b32 v19, v172, 6, v19
	v_and_b32_e32 v18, 32, v18
	v_bitop3_b32 v20, v19, s3, v18 bitop3:0xde
	s_lshl_b32 s3, s5, 5
	s_and_b32 s34, s3, 0x60
	s_lshl_b32 s3, s34, 7
	v_add_u32_e32 v0, v17, v15
	s_cmp_gt_i32 s2, 63
	v_add_lshl_u32 v0, v0, v16, 1
	v_mov_b32_e32 v1, v137
	s_waitcnt vmcnt(6)
	s_cselect_b64 s[36:37], -1, 0
	s_add_i32 s28, s48, -2
	v_lshl_add_u64 v[146:147], s[94:95], 0, v[0:1]
	v_add_u32_e32 v0, v14, v12
	s_cmpk_lt_u32 s4, 0x100
	v_add_lshl_u32 v0, v0, v13, 1
	v_bitop3_b32 v173, v19, s3, v18 bitop3:0xde
	s_cselect_b64 s[38:39], -1, 0
	s_ashr_i32 s93, s92, 31
	v_lshl_add_u64 v[148:149], s[94:95], 0, v[0:1]
	s_mov_b32 s30, 0
	v_add_u32_e32 v174, 0, v20
	s_mov_b32 s69, 0x10000
	s_barrier
	s_branch .LBB0_983

; #define PG8_STAGE(bufoff, gbase, voff) do { _Pragma("unroll") for (int _i = 0; _i < 2; ++_i) \
;         __builtin_amdgcn_global_load_lds((const unsigned*)((const char*)(gbase) + (voff)[_i]), (PG8_LAS unsigned*)(lds + (bufoff) + ldsw + _i * 8192), 16, 0, 0); } while (0)
; #define PG8_LDA(dst, b, h) do { _Pragma("unroll") for (int m = 0; m < 4; ++m) _Pragma("unroll") for (int k = 0; k < 2; ++k) dst[m][k] = *(const PG8_LAS bf16x8*)(lds + PG8_SA(b, h) + aoff + m * 2048 + k * 1024); } while (0)
; #define PG8_LDB(dst, b, h) do { _Pragma("unroll") for (int n = 0; n < 2; ++n) _Pragma("unroll") for (int k = 0; k < 2; ++k) dst[n][k] = *(const PG8_LAS bf16x8*)(lds + PG8_SB(b, h) + boff + n * 2048 + k * 1024); } while (0)
; #define PG8_MMA(ai, bj, At, Bt) do { __builtin_amdgcn_s_setprio(1); _Pragma("unroll") for (int m = 0; m < 4; ++m) _Pragma("unroll") for (int n = 0; n < 2; ++n) _Pragma("unroll") for (int k = 0; k < 2; ++k) \
;         acc[ai][bj][m][n] = __builtin_amdgcn_mfma_f32_16x16x32_bf16(Bt[n][k], At[m][k], acc[ai][bj][m][n], 0, 0, 0); __builtin_amdgcn_s_setprio(0); } while (0)
; #define PG8_WAIT_V(n) asm volatile("s_waitcnt vmcnt(" #n ")" ::: "memory")
; #define PG8_WAIT_L(n) asm volatile("s_waitcnt lgkmcnt(" #n ")" ::: "memory")
; #define PG8_BAR __builtin_amdgcn_s_barrier()
; #define PG8_SCHED __builtin_amdgcn_sched_barrier(0)
; template <class Epi, class Sched, bool ALIGN_EPI = false, bool SP2 = false>
; __device__ __forceinline__ void gemm_phase(PG8_LAS unsigned char* lds, const Gemm g, const Sched& S, const Epi& E, int tid_in) {
;     ...
;             PG8_LDB(B0, 0, 0); PG8_LDB(B1, 0, 1); PG8_SCHED; PG8_LDA(At, 0, 0); PG8_STAGE(PG8_SA(1, 1), a1 + hstep, voffA);
;             PG8_WAIT_V(8); PG8_WAIT_L(0); PG8_BAR; PG8_MMA(0, 0, At, B0); PG8_MMA(0, 1, At, B1); PG8_BAR; PG8_SCHED;
;             PG8_LDA(At, 0, 1); PG8_STAGE(PG8_SB(0, 0), b2, voffB); PG8_STAGE(PG8_SB(0, 1), b2 + hstep, voffB); PG8_STAGE(PG8_SA(0, 0), a2, voffA);
;             PG8_WAIT_V(8); PG8_WAIT_L(0); PG8_BAR; PG8_MMA(1, 0, At, B0); PG8_MMA(1, 1, At, B1); PG8_BAR; PG8_SCHED;
.LBB0_991:
	s_add_i32 vcc_lo, s40, 2
	s_add_u32 s12, s4, 0x80
	s_addc_u32 s13, s5, 0
	s_add_i32 vcc_hi, 0, 0x10000
	s_cmp_eq_u32 s28, s40
	s_cselect_b32 s41, s81, s13
	s_cselect_b32 s40, s80, s12
	v_add_u32_e32 v139, vcc_hi, v173
	s_cselect_b32 s13, s45, s43
	s_cselect_b32 s12, s44, s42
	s_add_i32 s69, 0, 0x14000
	ds_read_b128 v[96:99], v139
	ds_read_b128 v[104:107], v139 offset:1024
	ds_read_b128 v[150:153], v139 offset:2048
	ds_read_b128 v[154:157], v139 offset:3072
	v_add_u32_e32 v139, s69, v173
	ds_read_b128 v[158:161], v139
	ds_read_b128 v[162:165], v139 offset:1024
	ds_read_b128 v[176:179], v139 offset:2048
	ds_read_b128 v[180:183], v139 offset:3072
	v_lshl_add_u64 v[216:217], s[4:5], 0, v[146:147]
	s_add_i32 m0, s58, 0xc000
	ds_read_b128 v[184:187], v174
	ds_read_b128 v[188:191], v174 offset:1024
	ds_read_b128 v[192:195], v174 offset:2048
	ds_read_b128 v[196:199], v174 offset:3072
	ds_read_b128 v[200:203], v174 offset:4096
	ds_read_b128 v[204:207], v174 offset:5120
	ds_read_b128 v[208:211], v174 offset:6144
	ds_read_b128 v[212:215], v174 offset:7168
	global_load_lds_dwordx4 v[216:217], off
	v_lshl_add_u64 v[216:217], s[4:5], 0, v[148:149]
	s_add_i32 m0, s58, 0xe000
	s_nop 0
	global_load_lds_dwordx4 v[216:217], off
	s_waitcnt vmcnt(8)
	s_waitcnt lgkmcnt(0)
	s_barrier
	s_setprio 1
	s_waitcnt lgkmcnt(0)
	v_mfma_f32_16x16x32_bf16 v[132:135], v[96:99], v[184:187], v[132:135]
	v_mfma_f32_16x16x32_bf16 v[128:131], v[150:153], v[184:187], v[128:131]
	v_mfma_f32_16x16x32_bf16 v[124:127], v[96:99], v[192:195], v[124:127]
	v_mfma_f32_16x16x32_bf16 v[120:123], v[150:153], v[192:195], v[120:123]
	v_mfma_f32_16x16x32_bf16 v[116:119], v[96:99], v[200:203], v[116:119]
	v_mfma_f32_16x16x32_bf16 v[112:115], v[150:153], v[200:203], v[112:115]
	v_mfma_f32_16x16x32_bf16 v[108:111], v[96:99], v[208:211], v[108:111]
	v_mfma_f32_16x16x32_bf16 v[100:103], v[150:153], v[208:211], v[100:103]
	v_mfma_f32_16x16x32_bf16 v[132:135], v[104:107], v[188:191], v[132:135]
	v_mfma_f32_16x16x32_bf16 v[128:131], v[154:157], v[188:191], v[128:131]
	v_mfma_f32_16x16x32_bf16 v[124:127], v[104:107], v[196:199], v[124:127]
	v_mfma_f32_16x16x32_bf16 v[120:123], v[154:157], v[196:199], v[120:123]
	v_mfma_f32_16x16x32_bf16 v[116:119], v[104:107], v[204:207], v[116:119]
	v_mfma_f32_16x16x32_bf16 v[112:115], v[154:157], v[204:207], v[112:115]
	v_mfma_f32_16x16x32_bf16 v[108:111], v[104:107], v[212:215], v[108:111]
	v_mfma_f32_16x16x32_bf16 v[100:103], v[154:157], v[212:215], v[100:103]
	s_setprio 0
	s_setprio 1
	v_mfma_f32_16x16x32_bf16 v[60:63], v[158:161], v[184:187], v[60:63]
	v_mfma_f32_16x16x32_bf16 v[56:59], v[176:179], v[184:187], v[56:59]
	v_mfma_f32_16x16x32_bf16 v[52:55], v[158:161], v[192:195], v[52:55]
	v_mfma_f32_16x16x32_bf16 v[48:51], v[176:179], v[192:195], v[48:51]
	v_mfma_f32_16x16x32_bf16 v[44:47], v[158:161], v[200:203], v[44:47]
	v_mfma_f32_16x16x32_bf16 v[40:43], v[176:179], v[200:203], v[40:43]
	v_mfma_f32_16x16x32_bf16 v[36:39], v[158:161], v[208:211], v[36:39]
	v_mfma_f32_16x16x32_bf16 v[32:35], v[176:179], v[208:211], v[32:35]
	v_mfma_f32_16x16x32_bf16 v[60:63], v[162:165], v[188:191], v[60:63]
	v_mfma_f32_16x16x32_bf16 v[56:59], v[180:183], v[188:191], v[56:59]
	v_mfma_f32_16x16x32_bf16 v[52:55], v[162:165], v[196:199], v[52:55]
	v_mfma_f32_16x16x32_bf16 v[48:51], v[180:183], v[196:199], v[48:51]
	v_mfma_f32_16x16x32_bf16 v[44:47], v[162:165], v[204:207], v[44:47]
	v_mfma_f32_16x16x32_bf16 v[40:43], v[180:183], v[204:207], v[40:43]
	v_mfma_f32_16x16x32_bf16 v[36:39], v[162:165], v[212:215], v[36:39]
	v_mfma_f32_16x16x32_bf16 v[32:35], v[180:183], v[212:215], v[32:35]
	s_setprio 0
	s_barrier
	s_add_i32 vcc_hi, vcc_hi, s70
	v_lshl_add_u64 v[216:217], s[12:13], 0, v[136:137]
	s_mov_b32 m0, vcc_hi
	ds_read_b128 v[184:187], v174 offset:16384
	ds_read_b128 v[188:191], v174 offset:17408
	ds_read_b128 v[192:195], v174 offset:18432
	ds_read_b128 v[196:199], v174 offset:19456
	ds_read_b128 v[200:203], v174 offset:20480
	ds_read_b128 v[204:207], v174 offset:21504
	ds_read_b128 v[208:211], v174 offset:22528
	ds_read_b128 v[212:215], v174 offset:23552
	global_load_lds_dwordx4 v[216:217], off
	s_add_i32 m0, vcc_hi, 0x2000
	v_lshl_add_u64 v[218:219], s[12:13], 0, v[140:141]
	s_add_u32 s12, s12, s94
	s_addc_u32 s13, s13, s95
	s_add_i32 s69, s69, s70
	global_load_lds_dwordx4 v[218:219], off
	v_lshl_add_u64 v[220:221], s[12:13], 0, v[136:137]
	s_mov_b32 m0, s69
	v_lshl_add_u64 v[222:223], s[12:13], 0, v[140:141]
	global_load_lds_dwordx4 v[220:221], off
	s_add_i32 m0, s69, 0x2000
	v_lshl_add_u64 v[224:225], s[40:41], 0, v[144:145]
	global_load_lds_dwordx4 v[222:223], off
	s_mov_b32 m0, s58
	v_lshl_add_u64 v[226:227], s[40:41], 0, v[142:143]
	global_load_lds_dwordx4 v[224:225], off
	s_mov_b32 m0, s74
	s_nop 0
	global_load_lds_dwordx4 v[226:227], off
	s_waitcnt vmcnt(8)
	s_waitcnt lgkmcnt(0)
	s_barrier
; #define PG8_STAGE(bufoff, gbase, voff) do { _Pragma("unroll") for (int _i = 0; _i < 2; ++_i) \
;         __builtin_amdgcn_global_load_lds((const unsigned*)((const char*)(gbase) + (voff)[_i]), (PG8_LAS unsigned*)(lds + (bufoff) + ldsw + _i * 8192), 16, 0, 0); } while (0)
; #define PG8_LDA(dst, b, h) do { _Pragma("unroll") for (int m = 0; m < 4; ++m) _Pragma("unroll") for (int k = 0; k < 2; ++k) dst[m][k] = *(const PG8_LAS bf16x8*)(lds + PG8_SA(b, h) + aoff + m * 2048 + k * 1024); } while (0)
; #define PG8_LDB(dst, b, h) do { _Pragma("unroll") for (int n = 0; n < 2; ++n) _Pragma("unroll") for (int k = 0; k < 2; ++k) dst[n][k] = *(const PG8_LAS bf16x8*)(lds + PG8_SB(b, h) + boff + n * 2048 + k * 1024); } while (0)
; #define PG8_MMA(ai, bj, At, Bt) do { __builtin_amdgcn_s_setprio(1); _Pragma("unroll") for (int m = 0; m < 4; ++m) _Pragma("unroll") for (int n = 0; n < 2; ++n) _Pragma("unroll") for (int k = 0; k < 2; ++k) \
;         acc[ai][bj][m][n] = __builtin_amdgcn_mfma_f32_16x16x32_bf16(Bt[n][k], At[m][k], acc[ai][bj][m][n], 0, 0, 0); __builtin_amdgcn_s_setprio(0); } while (0)
; #define PG8_WAIT_V(n) asm volatile("s_waitcnt vmcnt(" #n ")" ::: "memory")
; #define PG8_WAIT_L(n) asm volatile("s_waitcnt lgkmcnt(" #n ")" ::: "memory")
; #define PG8_BAR __builtin_amdgcn_s_barrier()
; #define PG8_SCHED __builtin_amdgcn_sched_barrier(0)
; template <class Epi, class Sched, bool ALIGN_EPI = false, bool SP2 = false>
; __device__ __forceinline__ void gemm_phase(PG8_LAS unsigned char* lds, const Gemm g, const Sched& S, const Epi& E, int tid_in) {
;     ...
;             PG8_WAIT_V(8); PG8_WAIT_L(0); PG8_BAR; PG8_MMA(1, 0, At, B0); PG8_MMA(1, 1, At, B1); PG8_BAR; PG8_SCHED;
;             PG8_LDB(B0, 1, 0); PG8_LDB(B1, 1, 1); PG8_SCHED; PG8_LDA(At, 1, 0); PG8_STAGE(PG8_SA(0, 1), a2 + hstep, voffA);
;             PG8_WAIT_V(8); PG8_WAIT_L(0); PG8_BAR; PG8_MMA(0, 0, At, B0); PG8_MMA(0, 1, At, B1); PG8_BAR; PG8_SCHED;
	s_setprio 1
	s_waitcnt lgkmcnt(0)
	v_mfma_f32_16x16x32_bf16 v[92:95], v[96:99], v[184:187], v[92:95]
	v_mfma_f32_16x16x32_bf16 v[88:91], v[150:153], v[184:187], v[88:91]
	v_mfma_f32_16x16x32_bf16 v[84:87], v[96:99], v[192:195], v[84:87]
	v_mfma_f32_16x16x32_bf16 v[80:83], v[150:153], v[192:195], v[80:83]
	v_mfma_f32_16x16x32_bf16 v[76:79], v[96:99], v[200:203], v[76:79]
	v_mfma_f32_16x16x32_bf16 v[72:75], v[150:153], v[200:203], v[72:75]
	v_mfma_f32_16x16x32_bf16 v[68:71], v[96:99], v[208:211], v[68:71]
	v_mfma_f32_16x16x32_bf16 v[64:67], v[150:153], v[208:211], v[64:67]
	v_mfma_f32_16x16x32_bf16 v[92:95], v[104:107], v[188:191], v[92:95]
	v_mfma_f32_16x16x32_bf16 v[88:91], v[154:157], v[188:191], v[88:91]
	v_mfma_f32_16x16x32_bf16 v[84:87], v[104:107], v[196:199], v[84:87]
	v_mfma_f32_16x16x32_bf16 v[80:83], v[154:157], v[196:199], v[80:83]
	v_mfma_f32_16x16x32_bf16 v[76:79], v[104:107], v[204:207], v[76:79]
	v_mfma_f32_16x16x32_bf16 v[72:75], v[154:157], v[204:207], v[72:75]
	v_mfma_f32_16x16x32_bf16 v[68:71], v[104:107], v[212:215], v[68:71]
	v_mfma_f32_16x16x32_bf16 v[64:67], v[154:157], v[212:215], v[64:67]
	s_setprio 0
	s_setprio 1
	v_mfma_f32_16x16x32_bf16 v[28:31], v[158:161], v[184:187], v[28:31]
	v_mfma_f32_16x16x32_bf16 v[24:27], v[176:179], v[184:187], v[24:27]
	v_mfma_f32_16x16x32_bf16 v[20:23], v[158:161], v[192:195], v[20:23]
	v_mfma_f32_16x16x32_bf16 v[16:19], v[176:179], v[192:195], v[16:19]
	v_mfma_f32_16x16x32_bf16 v[12:15], v[158:161], v[200:203], v[12:15]
	v_mfma_f32_16x16x32_bf16 v[8:11], v[176:179], v[200:203], v[8:11]
	v_mfma_f32_16x16x32_bf16 v[4:7], v[158:161], v[208:211], v[4:7]
	v_mfma_f32_16x16x32_bf16 v[0:3], v[176:179], v[208:211], v[0:3]
	v_mfma_f32_16x16x32_bf16 v[28:31], v[162:165], v[188:191], v[28:31]
	v_mfma_f32_16x16x32_bf16 v[24:27], v[180:183], v[188:191], v[24:27]
	v_mfma_f32_16x16x32_bf16 v[20:23], v[162:165], v[196:199], v[20:23]
	v_mfma_f32_16x16x32_bf16 v[16:19], v[180:183], v[196:199], v[16:19]
	v_mfma_f32_16x16x32_bf16 v[12:15], v[162:165], v[204:207], v[12:15]
	v_mfma_f32_16x16x32_bf16 v[8:11], v[180:183], v[204:207], v[8:11]
	v_mfma_f32_16x16x32_bf16 v[4:7], v[162:165], v[212:215], v[4:7]
	v_mfma_f32_16x16x32_bf16 v[0:3], v[180:183], v[212:215], v[0:3]
	s_setprio 0
	s_barrier
	s_add_i32 s69, 0, 0x18000
	v_add_u32_e32 v139, s69, v173
	s_add_i32 vcc_hi, 0, 0x1c000
	ds_read_b128 v[96:99], v139
	ds_read_b128 v[104:107], v139 offset:1024
	ds_read_b128 v[150:153], v139 offset:2048
	ds_read_b128 v[154:157], v139 offset:3072
	v_add_u32_e32 v139, vcc_hi, v173
	ds_read_b128 v[158:161], v139
	ds_read_b128 v[162:165], v139 offset:1024
	ds_read_b128 v[176:179], v139 offset:2048
	ds_read_b128 v[180:183], v139 offset:3072
	s_add_u32 s12, s40, s94
	s_addc_u32 s13, s41, s95
	s_mov_b32 m0, s49
	v_lshl_add_u64 v[228:229], s[12:13], 0, v[144:145]
	ds_read_b128 v[184:187], v174 offset:32768
	ds_read_b128 v[188:191], v174 offset:33792
	ds_read_b128 v[192:195], v174 offset:34816
	ds_read_b128 v[196:199], v174 offset:35840
	ds_read_b128 v[200:203], v174 offset:36864
	ds_read_b128 v[204:207], v174 offset:37888
	ds_read_b128 v[208:211], v174 offset:38912
	ds_read_b128 v[212:215], v174 offset:39936
	global_load_lds_dwordx4 v[228:229], off
	v_lshl_add_u64 v[228:229], s[12:13], 0, v[142:143]
	s_mov_b32 m0, s77
	s_nop 0
	global_load_lds_dwordx4 v[228:229], off
	s_waitcnt vmcnt(8)
	s_waitcnt lgkmcnt(0)
	s_barrier
	s_setprio 1
	s_waitcnt lgkmcnt(0)
	v_mfma_f32_16x16x32_bf16 v[132:135], v[96:99], v[184:187], v[132:135]
	v_mfma_f32_16x16x32_bf16 v[128:131], v[150:153], v[184:187], v[128:131]
	v_mfma_f32_16x16x32_bf16 v[124:127], v[96:99], v[192:195], v[124:127]
	v_mfma_f32_16x16x32_bf16 v[120:123], v[150:153], v[192:195], v[120:123]
	v_mfma_f32_16x16x32_bf16 v[116:119], v[96:99], v[200:203], v[116:119]
	v_mfma_f32_16x16x32_bf16 v[112:115], v[150:153], v[200:203], v[112:115]
	v_mfma_f32_16x16x32_bf16 v[108:111], v[96:99], v[208:211], v[108:111]
	v_mfma_f32_16x16x32_bf16 v[100:103], v[150:153], v[208:211], v[100:103]
	v_mfma_f32_16x16x32_bf16 v[132:135], v[104:107], v[188:191], v[132:135]
	v_mfma_f32_16x16x32_bf16 v[128:131], v[154:157], v[188:191], v[128:131]
	v_mfma_f32_16x16x32_bf16 v[124:127], v[104:107], v[196:199], v[124:127]
	v_mfma_f32_16x16x32_bf16 v[120:123], v[154:157], v[196:199], v[120:123]
	v_mfma_f32_16x16x32_bf16 v[116:119], v[104:107], v[204:207], v[116:119]
	v_mfma_f32_16x16x32_bf16 v[112:115], v[154:157], v[204:207], v[112:115]
	v_mfma_f32_16x16x32_bf16 v[108:111], v[104:107], v[212:215], v[108:111]
	v_mfma_f32_16x16x32_bf16 v[100:103], v[154:157], v[212:215], v[100:103]
	s_setprio 0
	s_setprio 1
	v_mfma_f32_16x16x32_bf16 v[60:63], v[158:161], v[184:187], v[60:63]
	v_mfma_f32_16x16x32_bf16 v[56:59], v[176:179], v[184:187], v[56:59]
	v_mfma_f32_16x16x32_bf16 v[52:55], v[158:161], v[192:195], v[52:55]
	v_mfma_f32_16x16x32_bf16 v[48:51], v[176:179], v[192:195], v[48:51]
	v_mfma_f32_16x16x32_bf16 v[44:47], v[158:161], v[200:203], v[44:47]
	v_mfma_f32_16x16x32_bf16 v[40:43], v[176:179], v[200:203], v[40:43]
	v_mfma_f32_16x16x32_bf16 v[36:39], v[158:161], v[208:211], v[36:39]
	v_mfma_f32_16x16x32_bf16 v[32:35], v[176:179], v[208:211], v[32:35]
	v_mfma_f32_16x16x32_bf16 v[60:63], v[162:165], v[188:191], v[60:63]
	v_mfma_f32_16x16x32_bf16 v[56:59], v[180:183], v[188:191], v[56:59]
	v_mfma_f32_16x16x32_bf16 v[52:55], v[162:165], v[196:199], v[52:55]
	v_mfma_f32_16x16x32_bf16 v[48:51], v[180:183], v[196:199], v[48:51]
	v_mfma_f32_16x16x32_bf16 v[44:47], v[162:165], v[204:207], v[44:47]
	v_mfma_f32_16x16x32_bf16 v[40:43], v[180:183], v[204:207], v[40:43]
	v_mfma_f32_16x16x32_bf16 v[36:39], v[162:165], v[212:215], v[36:39]
	v_mfma_f32_16x16x32_bf16 v[32:35], v[180:183], v[212:215], v[32:35]
	s_setprio 0
	s_barrier
; #define PG8_STAGE(bufoff, gbase, voff) do { _Pragma("unroll") for (int _i = 0; _i < 2; ++_i) \
;         __builtin_amdgcn_global_load_lds((const unsigned*)((const char*)(gbase) + (voff)[_i]), (PG8_LAS unsigned*)(lds + (bufoff) + ldsw + _i * 8192), 16, 0, 0); } while (0)
; #define PG8_LDA(dst, b, h) do { _Pragma("unroll") for (int m = 0; m < 4; ++m) _Pragma("unroll") for (int k = 0; k < 2; ++k) dst[m][k] = *(const PG8_LAS bf16x8*)(lds + PG8_SA(b, h) + aoff + m * 2048 + k * 1024); } while (0)
; #define PG8_MMA(ai, bj, At, Bt) do { __builtin_amdgcn_s_setprio(1); _Pragma("unroll") for (int m = 0; m < 4; ++m) _Pragma("unroll") for (int n = 0; n < 2; ++n) _Pragma("unroll") for (int k = 0; k < 2; ++k) \
;         acc[ai][bj][m][n] = __builtin_amdgcn_mfma_f32_16x16x32_bf16(Bt[n][k], At[m][k], acc[ai][bj][m][n], 0, 0, 0); __builtin_amdgcn_s_setprio(0); } while (0)
; #define PG8_WAIT_V(n) asm volatile("s_waitcnt vmcnt(" #n ")" ::: "memory")
; #define PG8_WAIT_L(n) asm volatile("s_waitcnt lgkmcnt(" #n ")" ::: "memory")
; #define PG8_BAR __builtin_amdgcn_s_barrier()
; #define PG8_SCHED __builtin_amdgcn_sched_barrier(0)
; template <class Epi, class Sched, bool ALIGN_EPI = false, bool SP2 = false>
; __device__ __forceinline__ void gemm_phase(PG8_LAS unsigned char* lds, const Gemm g, const Sched& S, const Epi& E, int tid_in) {
;     ...
;         for (int t = 0; t < nt; t += 2) {
;     ...
;             PG8_LDA(At, 1, 1); PG8_STAGE(PG8_SB(1, 0), b3, voffB); PG8_STAGE(PG8_SB(1, 1), b3 + hstep, voffB); PG8_STAGE(PG8_SA(1, 0), a3, voffA);
;             PG8_WAIT_V(8); PG8_WAIT_L(0); PG8_BAR; PG8_MMA(1, 0, At, B0); PG8_MMA(1, 1, At, B1); PG8_BAR; PG8_SCHED;
	s_add_i32 s12, s69, s70
	v_lshl_add_u64 v[216:217], v[216:217], 0, s[52:53]
	s_mov_b32 m0, s12
	ds_read_b128 v[184:187], v174 offset:49152
	ds_read_b128 v[188:191], v174 offset:50176
	ds_read_b128 v[192:195], v174 offset:51200
	ds_read_b128 v[196:199], v174 offset:52224
	ds_read_b128 v[200:203], v174 offset:53248
	ds_read_b128 v[204:207], v174 offset:54272
	ds_read_b128 v[208:211], v174 offset:55296
	ds_read_b128 v[212:215], v174 offset:56320
	global_load_lds_dwordx4 v[216:217], off
	v_lshl_add_u64 v[216:217], v[218:219], 0, s[52:53]
	s_add_i32 m0, s12, 0x2000
	s_add_i32 s12, vcc_hi, s70
	global_load_lds_dwordx4 v[216:217], off
	v_lshl_add_u64 v[216:217], v[220:221], 0, s[52:53]
	s_mov_b32 m0, s12
	s_nop 0
	global_load_lds_dwordx4 v[216:217], off
	v_lshl_add_u64 v[216:217], v[222:223], 0, s[52:53]
	s_add_i32 m0, s12, 0x2000
	s_nop 0
	global_load_lds_dwordx4 v[216:217], off
	v_lshl_add_u64 v[216:217], v[224:225], 0, s[52:53]
	s_mov_b32 m0, s46
	s_nop 0
	global_load_lds_dwordx4 v[216:217], off
	v_lshl_add_u64 v[216:217], v[226:227], 0, s[52:53]
	s_mov_b32 m0, s19
	s_nop 0
	global_load_lds_dwordx4 v[216:217], off
	s_waitcnt vmcnt(8)
	s_waitcnt lgkmcnt(0)
	s_barrier
	s_setprio 1
	s_waitcnt lgkmcnt(0)
	v_mfma_f32_16x16x32_bf16 v[92:95], v[96:99], v[184:187], v[92:95]
	v_mfma_f32_16x16x32_bf16 v[88:91], v[150:153], v[184:187], v[88:91]
	v_mfma_f32_16x16x32_bf16 v[84:87], v[96:99], v[192:195], v[84:87]
	v_mfma_f32_16x16x32_bf16 v[80:83], v[150:153], v[192:195], v[80:83]
	v_mfma_f32_16x16x32_bf16 v[76:79], v[96:99], v[200:203], v[76:79]
	v_mfma_f32_16x16x32_bf16 v[72:75], v[150:153], v[200:203], v[72:75]
	v_mfma_f32_16x16x32_bf16 v[68:71], v[96:99], v[208:211], v[68:71]
	v_mfma_f32_16x16x32_bf16 v[64:67], v[150:153], v[208:211], v[64:67]
	v_mfma_f32_16x16x32_bf16 v[92:95], v[104:107], v[188:191], v[92:95]
	v_mfma_f32_16x16x32_bf16 v[88:91], v[154:157], v[188:191], v[88:91]
	v_mfma_f32_16x16x32_bf16 v[84:87], v[104:107], v[196:199], v[84:87]
	v_mfma_f32_16x16x32_bf16 v[80:83], v[154:157], v[196:199], v[80:83]
	v_mfma_f32_16x16x32_bf16 v[76:79], v[104:107], v[204:207], v[76:79]
	v_mfma_f32_16x16x32_bf16 v[72:75], v[154:157], v[204:207], v[72:75]
	v_mfma_f32_16x16x32_bf16 v[68:71], v[104:107], v[212:215], v[68:71]
	v_mfma_f32_16x16x32_bf16 v[64:67], v[154:157], v[212:215], v[64:67]
	s_setprio 0
	s_setprio 1
	v_mfma_f32_16x16x32_bf16 v[28:31], v[158:161], v[184:187], v[28:31]
	v_mfma_f32_16x16x32_bf16 v[24:27], v[176:179], v[184:187], v[24:27]
	v_mfma_f32_16x16x32_bf16 v[20:23], v[158:161], v[192:195], v[20:23]
	v_mfma_f32_16x16x32_bf16 v[16:19], v[176:179], v[192:195], v[16:19]
	v_mfma_f32_16x16x32_bf16 v[12:15], v[158:161], v[200:203], v[12:15]
	v_mfma_f32_16x16x32_bf16 v[8:11], v[176:179], v[200:203], v[8:11]
	v_mfma_f32_16x16x32_bf16 v[4:7], v[158:161], v[208:211], v[4:7]
	v_mfma_f32_16x16x32_bf16 v[0:3], v[176:179], v[208:211], v[0:3]
	v_mfma_f32_16x16x32_bf16 v[28:31], v[162:165], v[188:191], v[28:31]
	v_mfma_f32_16x16x32_bf16 v[24:27], v[180:183], v[188:191], v[24:27]
	v_mfma_f32_16x16x32_bf16 v[20:23], v[162:165], v[196:199], v[20:23]
	v_mfma_f32_16x16x32_bf16 v[16:19], v[180:183], v[196:199], v[16:19]
	v_mfma_f32_16x16x32_bf16 v[12:15], v[162:165], v[204:207], v[12:15]
	v_mfma_f32_16x16x32_bf16 v[8:11], v[180:183], v[204:207], v[8:11]
	v_mfma_f32_16x16x32_bf16 v[4:7], v[162:165], v[212:215], v[4:7]
	v_mfma_f32_16x16x32_bf16 v[0:3], v[180:183], v[212:215], v[0:3]
	s_add_u32 s4, s4, 0x100
	s_addc_u32 s5, s5, 0
	s_add_u32 s42, s42, 0x100
	s_addc_u32 s43, s43, 0
	s_cmp_ge_i32 vcc_lo, s48
	s_mov_b32 s40, vcc_lo
	s_setprio 0
	s_barrier
	s_cbranch_scc0 .LBB0_991
	s_mov_b32 s69, 0x10000

; #define PG8_STAGE(bufoff, gbase, voff) do { _Pragma("unroll") for (int _i = 0; _i < 2; ++_i) \
;         __builtin_amdgcn_global_load_lds((const unsigned*)((const char*)(gbase) + (voff)[_i]), (PG8_LAS unsigned*)(lds + (bufoff) + ldsw + _i * 8192), 16, 0, 0); } while (0)
; #define PG8_WAIT_V(n) asm volatile("s_waitcnt vmcnt(" #n ")" ::: "memory")
; #define PG8_BAR __builtin_amdgcn_s_barrier()
; template <class Epi, class Sched, bool ALIGN_EPI = false, bool SP2 = false>
; __device__ __forceinline__ void gemm_phase(PG8_LAS unsigned char* lds, const Gemm g, const Sched& S, const Epi& E, int tid_in) {
;     ...
;         PG8_STAGE(PG8_SB(0, 0), cB, voffB); PG8_STAGE(PG8_SB(0, 1), cB + hstep, voffB); PG8_STAGE(PG8_SA(0, 0), cA, voffA); PG8_STAGE(PG8_SA(0, 1), cA + hstep, voffA);
;         if (wr == 1) PG8_BAR;
;         PG8_WAIT_V(2); PG8_BAR;
;         PG8_STAGE(PG8_SB(1, 0), cB + kstep, voffB); PG8_STAGE(PG8_SA(1, 0), cA + kstep, voffA); PG8_STAGE(PG8_SB(1, 1), cB + hstep + kstep, voffB);
;         PG8_WAIT_V(6); PG8_BAR;
.LBB0_1233:
	s_add_u32 s14, s22, 0x5800000
	s_addc_u32 s15, s23, 0
	s_add_i32 m0, s45, 0x18000
	v_lshl_add_u64 v[0:1], v[0:1], 0, s[52:53]
	global_load_lds_dwordx4 v[0:1], off
	v_lshl_add_u64 v[0:1], v[2:3], 0, s[52:53]
	s_add_i32 m0, s45, 0x1a000
	s_add_i32 s58, s45, 0x8000
	global_load_lds_dwordx4 v[0:1], off
	v_lshl_add_u64 v[0:1], v[8:9], 0, s[52:53]
	s_mov_b32 m0, s58
	s_add_i32 s66, s45, 0xa000
	global_load_lds_dwordx4 v[0:1], off
	v_lshl_add_u64 v[0:1], v[10:11], 0, s[52:53]
	s_mov_b32 m0, s66
	v_bfe_u32 v146, v18, 4, 2
	global_load_lds_dwordx4 v[0:1], off
	s_add_i32 m0, s45, 0x1c000
	v_lshl_add_u64 v[0:1], v[4:5], 0, s[52:53]
	global_load_lds_dwordx4 v[0:1], off
	v_lshl_add_u64 v[0:1], v[6:7], 0, s[52:53]
	s_add_i32 m0, s45, 0x1e000
	s_lshr_b32 s3, s3, 26
	global_load_lds_dwordx4 v[0:1], off
	s_waitcnt vmcnt(8)
	s_barrier
	v_and_b32_e32 v147, 15, v18
	s_add_i32 s3, s2, s3
	v_lshlrev_b32_e32 v19, 4, v146
	v_lshlrev_b32_e32 v18, 2, v18
	s_ashr_i32 s49, s3, 6
	v_lshl_or_b32 v19, v147, 6, v19
	s_lshl_b32 s3, s7, 13
	v_and_b32_e32 v18, 32, v18
	v_bitop3_b32 v20, v19, s3, v18 bitop3:0xde
	s_lshl_b32 s3, s5, 5
	s_and_b32 s55, s3, 0x60
	s_lshl_b32 s54, s7, 6
	s_lshl_b32 s3, s55, 7
	v_add_u32_e32 v0, v17, v15
	s_cmp_gt_i32 s2, 63
	v_add_lshl_u32 v0, v0, v16, 1
	v_mov_b32_e32 v1, v137
	s_waitcnt vmcnt(6)
	s_cselect_b64 s[16:17], -1, 0
	s_add_i32 s70, s49, -2
	v_lshl_add_u64 v[134:135], s[8:9], 0, v[0:1]
	v_add_u32_e32 v0, v14, v12
	s_cmpk_lt_u32 s4, 0x100
	v_add_lshl_u32 v0, v0, v13, 1
	v_bitop3_b32 v148, v19, s3, v18 bitop3:0xde
	s_cselect_b64 s[24:25], -1, 0
	s_ashr_i32 s7, s6, 31
	v_lshl_add_u64 v[140:141], s[8:9], 0, v[0:1]
	s_mov_b32 s30, 0
	v_add_u32_e32 v149, 0, v20
	s_barrier
	s_branch .LBB0_1236

; #define PG8_STAGE(bufoff, gbase, voff) do { _Pragma("unroll") for (int _i = 0; _i < 2; ++_i) \
;         __builtin_amdgcn_global_load_lds((const unsigned*)((const char*)(gbase) + (voff)[_i]), (PG8_LAS unsigned*)(lds + (bufoff) + ldsw + _i * 8192), 16, 0, 0); } while (0)
; #define PG8_LDA(dst, b, h) do { _Pragma("unroll") for (int m = 0; m < 4; ++m) _Pragma("unroll") for (int k = 0; k < 2; ++k) dst[m][k] = *(const PG8_LAS bf16x8*)(lds + PG8_SA(b, h) + aoff + m * 2048 + k * 1024); } while (0)
; #define PG8_LDB(dst, b, h) do { _Pragma("unroll") for (int n = 0; n < 2; ++n) _Pragma("unroll") for (int k = 0; k < 2; ++k) dst[n][k] = *(const PG8_LAS bf16x8*)(lds + PG8_SB(b, h) + boff + n * 2048 + k * 1024); } while (0)
; #define PG8_MMA(ai, bj, At, Bt) do { __builtin_amdgcn_s_setprio(1); _Pragma("unroll") for (int m = 0; m < 4; ++m) _Pragma("unroll") for (int n = 0; n < 2; ++n) _Pragma("unroll") for (int k = 0; k < 2; ++k) \
;         acc[ai][bj][m][n] = __builtin_amdgcn_mfma_f32_16x16x32_bf16(Bt[n][k], At[m][k], acc[ai][bj][m][n], 0, 0, 0); __builtin_amdgcn_s_setprio(0); } while (0)
; #define PG8_WAIT_V(n) asm volatile("s_waitcnt vmcnt(" #n ")" ::: "memory")
; #define PG8_WAIT_L(n) asm volatile("s_waitcnt lgkmcnt(" #n ")" ::: "memory")
; #define PG8_BAR __builtin_amdgcn_s_barrier()
; #define PG8_SCHED __builtin_amdgcn_sched_barrier(0)
; template <class Epi, class Sched, bool ALIGN_EPI = false, bool SP2 = false>
; __device__ __forceinline__ void gemm_phase(PG8_LAS unsigned char* lds, const Gemm g, const Sched& S, const Epi& E, int tid_in) {
;     ...
;             PG8_LDB(B0, 0, 0); PG8_LDB(B1, 0, 1); PG8_SCHED; PG8_LDA(At, 0, 0); PG8_STAGE(PG8_SA(1, 1), a1 + hstep, voffA);
;             PG8_WAIT_V(8); PG8_WAIT_L(0); PG8_BAR; PG8_MMA(0, 0, At, B0); PG8_MMA(0, 1, At, B1); PG8_BAR; PG8_SCHED;
;             PG8_LDA(At, 0, 1); PG8_STAGE(PG8_SB(0, 0), b2, voffB); PG8_STAGE(PG8_SB(0, 1), b2 + hstep, voffB); PG8_STAGE(PG8_SA(0, 0), a2, voffA);
;             PG8_WAIT_V(8); PG8_WAIT_L(0); PG8_BAR; PG8_MMA(1, 0, At, B0); PG8_MMA(1, 1, At, B1); PG8_BAR; PG8_SCHED;
.LBB0_1244:
	s_add_i32 s80, s38, 2
	s_add_u32 s81, s36, 0x80
	s_addc_u32 s39, s37, 0
	s_add_i32 s83, 0, 0x10000
	s_cmp_eq_u32 s70, s38
	s_cselect_b32 s39, s5, s39
	s_cselect_b32 s38, s4, s81
	v_add_u32_e32 v139, s83, v148
	s_cselect_b32 s85, s27, s79
	s_cselect_b32 s84, s26, s33
	s_add_i32 s81, 0, 0x14000
	ds_read_b128 v[142:145], v139
	ds_read_b128 v[150:153], v139 offset:1024
	ds_read_b128 v[154:157], v139 offset:2048
	ds_read_b128 v[158:161], v139 offset:3072
	v_add_u32_e32 v139, s81, v148
	ds_read_b128 v[162:165], v139
	ds_read_b128 v[172:175], v139 offset:1024
	ds_read_b128 v[176:179], v139 offset:2048
	ds_read_b128 v[180:183], v139 offset:3072
	v_lshl_add_u64 v[216:217], s[36:37], 0, v[134:135]
	s_add_i32 m0, s45, 0xc000
	ds_read_b128 v[184:187], v149
	ds_read_b128 v[188:191], v149 offset:1024
	ds_read_b128 v[192:195], v149 offset:2048
	ds_read_b128 v[196:199], v149 offset:3072
	ds_read_b128 v[200:203], v149 offset:4096
	ds_read_b128 v[204:207], v149 offset:5120
	ds_read_b128 v[208:211], v149 offset:6144
	ds_read_b128 v[212:215], v149 offset:7168
	global_load_lds_dwordx4 v[216:217], off
	v_lshl_add_u64 v[216:217], s[36:37], 0, v[140:141]
	s_add_i32 m0, s45, 0xe000
	s_nop 0
	global_load_lds_dwordx4 v[216:217], off
	s_waitcnt vmcnt(8)
	s_waitcnt lgkmcnt(0)
	s_barrier
	s_setprio 1
	s_waitcnt lgkmcnt(0)
	v_mfma_f32_16x16x32_bf16 v[120:123], v[142:145], v[184:187], v[120:123]
	v_mfma_f32_16x16x32_bf16 v[124:127], v[154:157], v[184:187], v[124:127]
	v_mfma_f32_16x16x32_bf16 v[108:111], v[142:145], v[192:195], v[108:111]
	v_mfma_f32_16x16x32_bf16 v[104:107], v[154:157], v[192:195], v[104:107]
	v_mfma_f32_16x16x32_bf16 v[92:95], v[142:145], v[200:203], v[92:95]
	v_mfma_f32_16x16x32_bf16 v[88:91], v[154:157], v[200:203], v[88:91]
	v_mfma_f32_16x16x32_bf16 v[76:79], v[142:145], v[208:211], v[76:79]
	v_mfma_f32_16x16x32_bf16 v[72:75], v[154:157], v[208:211], v[72:75]
	v_mfma_f32_16x16x32_bf16 v[120:123], v[150:153], v[188:191], v[120:123]
	v_mfma_f32_16x16x32_bf16 v[124:127], v[158:161], v[188:191], v[124:127]
	v_mfma_f32_16x16x32_bf16 v[108:111], v[150:153], v[196:199], v[108:111]
	v_mfma_f32_16x16x32_bf16 v[104:107], v[158:161], v[196:199], v[104:107]
	v_mfma_f32_16x16x32_bf16 v[92:95], v[150:153], v[204:207], v[92:95]
	v_mfma_f32_16x16x32_bf16 v[88:91], v[158:161], v[204:207], v[88:91]
	v_mfma_f32_16x16x32_bf16 v[76:79], v[150:153], v[212:215], v[76:79]
	v_mfma_f32_16x16x32_bf16 v[72:75], v[158:161], v[212:215], v[72:75]
	s_setprio 0
	s_setprio 1
	v_mfma_f32_16x16x32_bf16 v[116:119], v[162:165], v[184:187], v[116:119]
	v_mfma_f32_16x16x32_bf16 v[112:115], v[176:179], v[184:187], v[112:115]
	v_mfma_f32_16x16x32_bf16 v[100:103], v[162:165], v[192:195], v[100:103]
	v_mfma_f32_16x16x32_bf16 v[96:99], v[176:179], v[192:195], v[96:99]
	v_mfma_f32_16x16x32_bf16 v[84:87], v[162:165], v[200:203], v[84:87]
	v_mfma_f32_16x16x32_bf16 v[80:83], v[176:179], v[200:203], v[80:83]
	v_mfma_f32_16x16x32_bf16 v[68:71], v[162:165], v[208:211], v[68:71]
	v_mfma_f32_16x16x32_bf16 v[64:67], v[176:179], v[208:211], v[64:67]
	v_mfma_f32_16x16x32_bf16 v[116:119], v[172:175], v[188:191], v[116:119]
	v_mfma_f32_16x16x32_bf16 v[112:115], v[180:183], v[188:191], v[112:115]
	v_mfma_f32_16x16x32_bf16 v[100:103], v[172:175], v[196:199], v[100:103]
	v_mfma_f32_16x16x32_bf16 v[96:99], v[180:183], v[196:199], v[96:99]
	v_mfma_f32_16x16x32_bf16 v[84:87], v[172:175], v[204:207], v[84:87]
	v_mfma_f32_16x16x32_bf16 v[80:83], v[180:183], v[204:207], v[80:83]
	v_mfma_f32_16x16x32_bf16 v[68:71], v[172:175], v[212:215], v[68:71]
	v_mfma_f32_16x16x32_bf16 v[64:67], v[180:183], v[212:215], v[64:67]
	s_setprio 0
	s_barrier
	s_add_i32 s83, s83, s29
	v_lshl_add_u64 v[216:217], s[84:85], 0, v[136:137]
	s_mov_b32 m0, s83
	ds_read_b128 v[184:187], v149 offset:16384
	ds_read_b128 v[188:191], v149 offset:17408
	ds_read_b128 v[192:195], v149 offset:18432
	ds_read_b128 v[196:199], v149 offset:19456
	ds_read_b128 v[200:203], v149 offset:20480
	ds_read_b128 v[204:207], v149 offset:21504
	ds_read_b128 v[208:211], v149 offset:22528
	ds_read_b128 v[212:215], v149 offset:23552
	global_load_lds_dwordx4 v[216:217], off
	s_add_i32 m0, s83, 0x2000
	v_lshl_add_u64 v[218:219], s[84:85], 0, v[128:129]
	s_add_u32 s84, s84, s8
	s_addc_u32 s85, s85, s9
	s_add_i32 s81, s81, s29
	global_load_lds_dwordx4 v[218:219], off
	v_lshl_add_u64 v[220:221], s[84:85], 0, v[136:137]
	s_mov_b32 m0, s81
	v_lshl_add_u64 v[222:223], s[84:85], 0, v[128:129]
	global_load_lds_dwordx4 v[220:221], off
	s_add_i32 m0, s81, 0x2000
	v_lshl_add_u64 v[224:225], s[38:39], 0, v[132:133]
	global_load_lds_dwordx4 v[222:223], off
	s_mov_b32 m0, s45
	v_lshl_add_u64 v[226:227], s[38:39], 0, v[130:131]
	global_load_lds_dwordx4 v[224:225], off
	s_mov_b32 m0, s46
	s_nop 0
	global_load_lds_dwordx4 v[226:227], off
	s_waitcnt vmcnt(8)
	s_waitcnt lgkmcnt(0)
	s_barrier
; #define PG8_STAGE(bufoff, gbase, voff) do { _Pragma("unroll") for (int _i = 0; _i < 2; ++_i) \
;         __builtin_amdgcn_global_load_lds((const unsigned*)((const char*)(gbase) + (voff)[_i]), (PG8_LAS unsigned*)(lds + (bufoff) + ldsw + _i * 8192), 16, 0, 0); } while (0)
; #define PG8_LDA(dst, b, h) do { _Pragma("unroll") for (int m = 0; m < 4; ++m) _Pragma("unroll") for (int k = 0; k < 2; ++k) dst[m][k] = *(const PG8_LAS bf16x8*)(lds + PG8_SA(b, h) + aoff + m * 2048 + k * 1024); } while (0)
; #define PG8_LDB(dst, b, h) do { _Pragma("unroll") for (int n = 0; n < 2; ++n) _Pragma("unroll") for (int k = 0; k < 2; ++k) dst[n][k] = *(const PG8_LAS bf16x8*)(lds + PG8_SB(b, h) + boff + n * 2048 + k * 1024); } while (0)
; #define PG8_MMA(ai, bj, At, Bt) do { __builtin_amdgcn_s_setprio(1); _Pragma("unroll") for (int m = 0; m < 4; ++m) _Pragma("unroll") for (int n = 0; n < 2; ++n) _Pragma("unroll") for (int k = 0; k < 2; ++k) \
;         acc[ai][bj][m][n] = __builtin_amdgcn_mfma_f32_16x16x32_bf16(Bt[n][k], At[m][k], acc[ai][bj][m][n], 0, 0, 0); __builtin_amdgcn_s_setprio(0); } while (0)
; #define PG8_WAIT_V(n) asm volatile("s_waitcnt vmcnt(" #n ")" ::: "memory")
; #define PG8_WAIT_L(n) asm volatile("s_waitcnt lgkmcnt(" #n ")" ::: "memory")
; #define PG8_BAR __builtin_amdgcn_s_barrier()
; #define PG8_SCHED __builtin_amdgcn_sched_barrier(0)
; template <class Epi, class Sched, bool ALIGN_EPI = false, bool SP2 = false>
; __device__ __forceinline__ void gemm_phase(PG8_LAS unsigned char* lds, const Gemm g, const Sched& S, const Epi& E, int tid_in) {
;     ...
;             PG8_WAIT_V(8); PG8_WAIT_L(0); PG8_BAR; PG8_MMA(1, 0, At, B0); PG8_MMA(1, 1, At, B1); PG8_BAR; PG8_SCHED;
;             PG8_LDB(B0, 1, 0); PG8_LDB(B1, 1, 1); PG8_SCHED; PG8_LDA(At, 1, 0); PG8_STAGE(PG8_SA(0, 1), a2 + hstep, voffA);
;             PG8_WAIT_V(8); PG8_WAIT_L(0); PG8_BAR; PG8_MMA(0, 0, At, B0); PG8_MMA(0, 1, At, B1); PG8_BAR; PG8_SCHED;
	s_setprio 1
	s_waitcnt lgkmcnt(0)
	v_mfma_f32_16x16x32_bf16 v[60:63], v[142:145], v[184:187], v[60:63]
	v_mfma_f32_16x16x32_bf16 v[56:59], v[154:157], v[184:187], v[56:59]
	v_mfma_f32_16x16x32_bf16 v[44:47], v[142:145], v[192:195], v[44:47]
	v_mfma_f32_16x16x32_bf16 v[40:43], v[154:157], v[192:195], v[40:43]
	v_mfma_f32_16x16x32_bf16 v[28:31], v[142:145], v[200:203], v[28:31]
	v_mfma_f32_16x16x32_bf16 v[24:27], v[154:157], v[200:203], v[24:27]
	v_mfma_f32_16x16x32_bf16 v[12:15], v[142:145], v[208:211], v[12:15]
	v_mfma_f32_16x16x32_bf16 v[8:11], v[154:157], v[208:211], v[8:11]
	v_mfma_f32_16x16x32_bf16 v[60:63], v[150:153], v[188:191], v[60:63]
	v_mfma_f32_16x16x32_bf16 v[56:59], v[158:161], v[188:191], v[56:59]
	v_mfma_f32_16x16x32_bf16 v[44:47], v[150:153], v[196:199], v[44:47]
	v_mfma_f32_16x16x32_bf16 v[40:43], v[158:161], v[196:199], v[40:43]
	v_mfma_f32_16x16x32_bf16 v[28:31], v[150:153], v[204:207], v[28:31]
	v_mfma_f32_16x16x32_bf16 v[24:27], v[158:161], v[204:207], v[24:27]
	v_mfma_f32_16x16x32_bf16 v[12:15], v[150:153], v[212:215], v[12:15]
	v_mfma_f32_16x16x32_bf16 v[8:11], v[158:161], v[212:215], v[8:11]
	s_setprio 0
	s_setprio 1
	v_mfma_f32_16x16x32_bf16 v[52:55], v[162:165], v[184:187], v[52:55]
	v_mfma_f32_16x16x32_bf16 v[48:51], v[176:179], v[184:187], v[48:51]
	v_mfma_f32_16x16x32_bf16 v[36:39], v[162:165], v[192:195], v[36:39]
	v_mfma_f32_16x16x32_bf16 v[32:35], v[176:179], v[192:195], v[32:35]
	v_mfma_f32_16x16x32_bf16 v[20:23], v[162:165], v[200:203], v[20:23]
	v_mfma_f32_16x16x32_bf16 v[16:19], v[176:179], v[200:203], v[16:19]
	v_mfma_f32_16x16x32_bf16 v[4:7], v[162:165], v[208:211], v[4:7]
	v_mfma_f32_16x16x32_bf16 v[0:3], v[176:179], v[208:211], v[0:3]
	v_mfma_f32_16x16x32_bf16 v[52:55], v[172:175], v[188:191], v[52:55]
	v_mfma_f32_16x16x32_bf16 v[48:51], v[180:183], v[188:191], v[48:51]
	v_mfma_f32_16x16x32_bf16 v[36:39], v[172:175], v[196:199], v[36:39]
	v_mfma_f32_16x16x32_bf16 v[32:35], v[180:183], v[196:199], v[32:35]
	v_mfma_f32_16x16x32_bf16 v[20:23], v[172:175], v[204:207], v[20:23]
	v_mfma_f32_16x16x32_bf16 v[16:19], v[180:183], v[204:207], v[16:19]
	v_mfma_f32_16x16x32_bf16 v[4:7], v[172:175], v[212:215], v[4:7]
	v_mfma_f32_16x16x32_bf16 v[0:3], v[180:183], v[212:215], v[0:3]
	s_setprio 0
	s_barrier
	s_add_i32 s81, 0, 0x18000
	v_add_u32_e32 v139, s81, v148
	s_add_i32 s83, 0, 0x1c000
	ds_read_b128 v[142:145], v139
	ds_read_b128 v[150:153], v139 offset:1024
	ds_read_b128 v[154:157], v139 offset:2048
	ds_read_b128 v[158:161], v139 offset:3072
	v_add_u32_e32 v139, s83, v148
	ds_read_b128 v[162:165], v139
	ds_read_b128 v[172:175], v139 offset:1024
	ds_read_b128 v[176:179], v139 offset:2048
	ds_read_b128 v[180:183], v139 offset:3072
	s_add_u32 s38, s38, s8
	s_addc_u32 s39, s39, s9
	s_mov_b32 m0, s47
	v_lshl_add_u64 v[228:229], s[38:39], 0, v[132:133]
	ds_read_b128 v[184:187], v149 offset:32768
	ds_read_b128 v[188:191], v149 offset:33792
	ds_read_b128 v[192:195], v149 offset:34816
	ds_read_b128 v[196:199], v149 offset:35840
	ds_read_b128 v[200:203], v149 offset:36864
	ds_read_b128 v[204:207], v149 offset:37888
	ds_read_b128 v[208:211], v149 offset:38912
	ds_read_b128 v[212:215], v149 offset:39936
	global_load_lds_dwordx4 v[228:229], off
	v_lshl_add_u64 v[228:229], s[38:39], 0, v[130:131]
	s_mov_b32 m0, s48
	s_nop 0
	global_load_lds_dwordx4 v[228:229], off
	s_waitcnt vmcnt(8)
	s_waitcnt lgkmcnt(0)
	s_barrier
	s_setprio 1
	s_waitcnt lgkmcnt(0)
	v_mfma_f32_16x16x32_bf16 v[120:123], v[142:145], v[184:187], v[120:123]
	v_mfma_f32_16x16x32_bf16 v[124:127], v[154:157], v[184:187], v[124:127]
	v_mfma_f32_16x16x32_bf16 v[108:111], v[142:145], v[192:195], v[108:111]
	v_mfma_f32_16x16x32_bf16 v[104:107], v[154:157], v[192:195], v[104:107]
	v_mfma_f32_16x16x32_bf16 v[92:95], v[142:145], v[200:203], v[92:95]
	v_mfma_f32_16x16x32_bf16 v[88:91], v[154:157], v[200:203], v[88:91]
	v_mfma_f32_16x16x32_bf16 v[76:79], v[142:145], v[208:211], v[76:79]
	v_mfma_f32_16x16x32_bf16 v[72:75], v[154:157], v[208:211], v[72:75]
	v_mfma_f32_16x16x32_bf16 v[120:123], v[150:153], v[188:191], v[120:123]
	v_mfma_f32_16x16x32_bf16 v[124:127], v[158:161], v[188:191], v[124:127]
	v_mfma_f32_16x16x32_bf16 v[108:111], v[150:153], v[196:199], v[108:111]
	v_mfma_f32_16x16x32_bf16 v[104:107], v[158:161], v[196:199], v[104:107]
	v_mfma_f32_16x16x32_bf16 v[92:95], v[150:153], v[204:207], v[92:95]
	v_mfma_f32_16x16x32_bf16 v[88:91], v[158:161], v[204:207], v[88:91]
	v_mfma_f32_16x16x32_bf16 v[76:79], v[150:153], v[212:215], v[76:79]
	v_mfma_f32_16x16x32_bf16 v[72:75], v[158:161], v[212:215], v[72:75]
	s_setprio 0
	s_setprio 1
	v_mfma_f32_16x16x32_bf16 v[116:119], v[162:165], v[184:187], v[116:119]
	v_mfma_f32_16x16x32_bf16 v[112:115], v[176:179], v[184:187], v[112:115]
	v_mfma_f32_16x16x32_bf16 v[100:103], v[162:165], v[192:195], v[100:103]
	v_mfma_f32_16x16x32_bf16 v[96:99], v[176:179], v[192:195], v[96:99]
	v_mfma_f32_16x16x32_bf16 v[84:87], v[162:165], v[200:203], v[84:87]
	v_mfma_f32_16x16x32_bf16 v[80:83], v[176:179], v[200:203], v[80:83]
	v_mfma_f32_16x16x32_bf16 v[68:71], v[162:165], v[208:211], v[68:71]
	v_mfma_f32_16x16x32_bf16 v[64:67], v[176:179], v[208:211], v[64:67]
	v_mfma_f32_16x16x32_bf16 v[116:119], v[172:175], v[188:191], v[116:119]
	v_mfma_f32_16x16x32_bf16 v[112:115], v[180:183], v[188:191], v[112:115]
	v_mfma_f32_16x16x32_bf16 v[100:103], v[172:175], v[196:199], v[100:103]
	v_mfma_f32_16x16x32_bf16 v[96:99], v[180:183], v[196:199], v[96:99]
	v_mfma_f32_16x16x32_bf16 v[84:87], v[172:175], v[204:207], v[84:87]
	v_mfma_f32_16x16x32_bf16 v[80:83], v[180:183], v[204:207], v[80:83]
	v_mfma_f32_16x16x32_bf16 v[68:71], v[172:175], v[212:215], v[68:71]
	v_mfma_f32_16x16x32_bf16 v[64:67], v[180:183], v[212:215], v[64:67]
	s_setprio 0
	s_barrier
; #define PG8_STAGE(bufoff, gbase, voff) do { _Pragma("unroll") for (int _i = 0; _i < 2; ++_i) \
;         __builtin_amdgcn_global_load_lds((const unsigned*)((const char*)(gbase) + (voff)[_i]), (PG8_LAS unsigned*)(lds + (bufoff) + ldsw + _i * 8192), 16, 0, 0); } while (0)
; #define PG8_LDA(dst, b, h) do { _Pragma("unroll") for (int m = 0; m < 4; ++m) _Pragma("unroll") for (int k = 0; k < 2; ++k) dst[m][k] = *(const PG8_LAS bf16x8*)(lds + PG8_SA(b, h) + aoff + m * 2048 + k * 1024); } while (0)
; #define PG8_MMA(ai, bj, At, Bt) do { __builtin_amdgcn_s_setprio(1); _Pragma("unroll") for (int m = 0; m < 4; ++m) _Pragma("unroll") for (int n = 0; n < 2; ++n) _Pragma("unroll") for (int k = 0; k < 2; ++k) \
;         acc[ai][bj][m][n] = __builtin_amdgcn_mfma_f32_16x16x32_bf16(Bt[n][k], At[m][k], acc[ai][bj][m][n], 0, 0, 0); __builtin_amdgcn_s_setprio(0); } while (0)
; #define PG8_WAIT_V(n) asm volatile("s_waitcnt vmcnt(" #n ")" ::: "memory")
; #define PG8_WAIT_L(n) asm volatile("s_waitcnt lgkmcnt(" #n ")" ::: "memory")
; #define PG8_BAR __builtin_amdgcn_s_barrier()
; #define PG8_SCHED __builtin_amdgcn_sched_barrier(0)
; template <class Epi, class Sched, bool ALIGN_EPI = false, bool SP2 = false>
; __device__ __forceinline__ void gemm_phase(PG8_LAS unsigned char* lds, const Gemm g, const Sched& S, const Epi& E, int tid_in) {
;     ...
;         for (int t = 0; t < nt; t += 2) {
;     ...
;             PG8_LDA(At, 1, 1); PG8_STAGE(PG8_SB(1, 0), b3, voffB); PG8_STAGE(PG8_SB(1, 1), b3 + hstep, voffB); PG8_STAGE(PG8_SA(1, 0), a3, voffA);
;             PG8_WAIT_V(8); PG8_WAIT_L(0); PG8_BAR; PG8_MMA(1, 0, At, B0); PG8_MMA(1, 1, At, B1); PG8_BAR; PG8_SCHED;
	s_add_i32 s38, s81, s29
	v_lshl_add_u64 v[216:217], v[216:217], 0, s[52:53]
	s_mov_b32 m0, s38
	ds_read_b128 v[184:187], v149 offset:49152
	ds_read_b128 v[188:191], v149 offset:50176
	ds_read_b128 v[192:195], v149 offset:51200
	ds_read_b128 v[196:199], v149 offset:52224
	ds_read_b128 v[200:203], v149 offset:53248
	ds_read_b128 v[204:207], v149 offset:54272
	ds_read_b128 v[208:211], v149 offset:55296
	ds_read_b128 v[212:215], v149 offset:56320
	global_load_lds_dwordx4 v[216:217], off
	v_lshl_add_u64 v[216:217], v[218:219], 0, s[52:53]
	s_add_i32 m0, s38, 0x2000
	s_add_i32 s38, s83, s29
	global_load_lds_dwordx4 v[216:217], off
	v_lshl_add_u64 v[216:217], v[220:221], 0, s[52:53]
	s_mov_b32 m0, s38
	s_nop 0
	global_load_lds_dwordx4 v[216:217], off
	v_lshl_add_u64 v[216:217], v[222:223], 0, s[52:53]
	s_add_i32 m0, s38, 0x2000
	s_nop 0
	global_load_lds_dwordx4 v[216:217], off
	v_lshl_add_u64 v[216:217], v[224:225], 0, s[52:53]
	s_mov_b32 m0, s58
	s_nop 0
	global_load_lds_dwordx4 v[216:217], off
	v_lshl_add_u64 v[216:217], v[226:227], 0, s[52:53]
	s_mov_b32 m0, s66
	s_nop 0
	global_load_lds_dwordx4 v[216:217], off
	s_waitcnt vmcnt(8)
	s_waitcnt lgkmcnt(0)
	s_barrier
	s_setprio 1
	s_waitcnt lgkmcnt(0)
	v_mfma_f32_16x16x32_bf16 v[60:63], v[142:145], v[184:187], v[60:63]
	v_mfma_f32_16x16x32_bf16 v[56:59], v[154:157], v[184:187], v[56:59]
	v_mfma_f32_16x16x32_bf16 v[44:47], v[142:145], v[192:195], v[44:47]
	v_mfma_f32_16x16x32_bf16 v[40:43], v[154:157], v[192:195], v[40:43]
	v_mfma_f32_16x16x32_bf16 v[28:31], v[142:145], v[200:203], v[28:31]
	v_mfma_f32_16x16x32_bf16 v[24:27], v[154:157], v[200:203], v[24:27]
	v_mfma_f32_16x16x32_bf16 v[12:15], v[142:145], v[208:211], v[12:15]
	v_mfma_f32_16x16x32_bf16 v[8:11], v[154:157], v[208:211], v[8:11]
	v_mfma_f32_16x16x32_bf16 v[60:63], v[150:153], v[188:191], v[60:63]
	v_mfma_f32_16x16x32_bf16 v[56:59], v[158:161], v[188:191], v[56:59]
	v_mfma_f32_16x16x32_bf16 v[44:47], v[150:153], v[196:199], v[44:47]
	v_mfma_f32_16x16x32_bf16 v[40:43], v[158:161], v[196:199], v[40:43]
	v_mfma_f32_16x16x32_bf16 v[28:31], v[150:153], v[204:207], v[28:31]
	v_mfma_f32_16x16x32_bf16 v[24:27], v[158:161], v[204:207], v[24:27]
	v_mfma_f32_16x16x32_bf16 v[12:15], v[150:153], v[212:215], v[12:15]
	v_mfma_f32_16x16x32_bf16 v[8:11], v[158:161], v[212:215], v[8:11]
	s_setprio 0
	s_setprio 1
	v_mfma_f32_16x16x32_bf16 v[52:55], v[162:165], v[184:187], v[52:55]
	v_mfma_f32_16x16x32_bf16 v[48:51], v[176:179], v[184:187], v[48:51]
	v_mfma_f32_16x16x32_bf16 v[36:39], v[162:165], v[192:195], v[36:39]
	v_mfma_f32_16x16x32_bf16 v[32:35], v[176:179], v[192:195], v[32:35]
	v_mfma_f32_16x16x32_bf16 v[20:23], v[162:165], v[200:203], v[20:23]
	v_mfma_f32_16x16x32_bf16 v[16:19], v[176:179], v[200:203], v[16:19]
	v_mfma_f32_16x16x32_bf16 v[4:7], v[162:165], v[208:211], v[4:7]
	v_mfma_f32_16x16x32_bf16 v[0:3], v[176:179], v[208:211], v[0:3]
	v_mfma_f32_16x16x32_bf16 v[52:55], v[172:175], v[188:191], v[52:55]
	v_mfma_f32_16x16x32_bf16 v[48:51], v[180:183], v[188:191], v[48:51]
	v_mfma_f32_16x16x32_bf16 v[36:39], v[172:175], v[196:199], v[36:39]
	v_mfma_f32_16x16x32_bf16 v[32:35], v[180:183], v[196:199], v[32:35]
	v_mfma_f32_16x16x32_bf16 v[20:23], v[172:175], v[204:207], v[20:23]
	v_mfma_f32_16x16x32_bf16 v[16:19], v[180:183], v[204:207], v[16:19]
	v_mfma_f32_16x16x32_bf16 v[4:7], v[172:175], v[212:215], v[4:7]
	v_mfma_f32_16x16x32_bf16 v[0:3], v[180:183], v[212:215], v[0:3]
	s_add_u32 s36, s36, 0x100
	s_addc_u32 s37, s37, 0
	s_add_u32 s33, s33, 0x100
	s_addc_u32 s79, s79, 0
	s_cmp_ge_i32 s80, s49
	s_mov_b32 s38, s80
	s_setprio 0
	s_barrier
	s_cbranch_scc0 .LBB0_1244

; #define PG8_STAGE(bufoff, gbase, voff) do { _Pragma("unroll") for (int _i = 0; _i < 2; ++_i) \
;         __builtin_amdgcn_global_load_lds((const unsigned*)((const char*)(gbase) + (voff)[_i]), (PG8_LAS unsigned*)(lds + (bufoff) + ldsw + _i * 8192), 16, 0, 0); } while (0)
; #define PG8_WAIT_V(n) asm volatile("s_waitcnt vmcnt(" #n ")" ::: "memory")
; #define PG8_BAR __builtin_amdgcn_s_barrier()
; template <class Epi, class Sched, bool ALIGN_EPI = false, bool SP2 = false>
; __device__ __forceinline__ void gemm_phase(PG8_LAS unsigned char* lds, const Gemm g, const Sched& S, const Epi& E, int tid_in) {
;     ...
;         PG8_STAGE(PG8_SB(0, 0), cB, voffB); PG8_STAGE(PG8_SB(0, 1), cB + hstep, voffB); PG8_STAGE(PG8_SA(0, 0), cA, voffA); PG8_STAGE(PG8_SA(0, 1), cA + hstep, voffA);
;         if (wr == 1) PG8_BAR;
;         PG8_WAIT_V(2); PG8_BAR;
;         PG8_STAGE(PG8_SB(1, 0), cB + kstep, voffB); PG8_STAGE(PG8_SA(1, 0), cA + kstep, voffA); PG8_STAGE(PG8_SB(1, 1), cB + hstep + kstep, voffB);
;         PG8_WAIT_V(6); PG8_BAR;
.LBB0_1571:
	v_readlane_b32 s20, v254, 36
	s_add_i32 s11, s61, s20
	s_not_b32 s11, s11
	s_lshl_b32 s11, s11, 20
	s_and_b32 s11, s11, 0x100000
	v_readlane_b32 s20, v254, 61
	v_readlane_b32 s21, v254, 37
	s_add_u32 s20, s20, s11
	v_readlane_b32 s11, v254, 62
	s_addc_u32 s21, s11, 0
	s_add_i32 m0, s29, 0x18000
	v_lshl_add_u64 v[0:1], v[0:1], 0, s[52:53]
	global_load_lds_dwordx4 v[0:1], off
	v_lshl_add_u64 v[0:1], v[2:3], 0, s[52:53]
	s_add_i32 m0, s29, 0x1a000
	s_add_i32 s48, s29, 0x8000
	global_load_lds_dwordx4 v[0:1], off
	v_lshl_add_u64 v[0:1], v[8:9], 0, s[52:53]
	s_mov_b32 m0, s48
	s_add_i32 s49, s29, 0xa000
	global_load_lds_dwordx4 v[0:1], off
	v_lshl_add_u64 v[0:1], v[10:11], 0, s[52:53]
	s_mov_b32 m0, s49
	v_bfe_u32 v148, v18, 4, 2
	global_load_lds_dwordx4 v[0:1], off
	s_add_i32 m0, s29, 0x1c000
	v_lshl_add_u64 v[0:1], v[4:5], 0, s[52:53]
	global_load_lds_dwordx4 v[0:1], off
	v_lshl_add_u64 v[0:1], v[6:7], 0, s[52:53]
	s_add_i32 m0, s29, 0x1e000
	s_lshr_b32 s3, s3, 26
	global_load_lds_dwordx4 v[0:1], off
	s_waitcnt vmcnt(8)
	s_barrier
	v_and_b32_e32 v149, 15, v18
	s_add_i32 s3, s2, s3
	v_lshlrev_b32_e32 v19, 4, v148
	v_lshlrev_b32_e32 v18, 2, v18
	s_and_b32 s44, s4, 3
	s_ashr_i32 s45, s3, 6
	v_lshl_or_b32 v19, v149, 6, v19
	s_lshl_b32 s3, s5, 13
	v_and_b32_e32 v18, 32, v18
	s_lshl_b32 s46, s5, 6
	v_bitop3_b32 v20, v19, s3, v18 bitop3:0xde
	s_lshl_b32 s47, s44, 5
	s_lshl_b32 s3, s44, 12
	s_cmp_gt_i32 s2, 63
	s_cselect_b64 s[22:23], -1, 0
	s_add_i32 s54, s45, -2
	s_cmpk_lt_u32 s7, 0x100
	s_cselect_b64 s[24:25], -1, 0
	s_lshl_b32 s58, s30, 3
	s_abs_i32 s70, s58
	v_cvt_f32_u32_e32 v0, s70
	v_bitop3_b32 v150, v19, s3, v18 bitop3:0xde
	s_sub_i32 s2, 0, s70
	v_mov_b32_e32 v1, v137
	v_rcp_iflag_f32_e32 v0, v0
	s_waitcnt vmcnt(6)
	s_ashr_i32 s55, s19, 31
	s_ashr_i32 s11, s10, 31
	v_mul_f32_e32 v0, 0x4f7ffffe, v0
	v_cvt_u32_f32_e32 v0, v0
	s_mov_b32 s7, s6
	s_mov_b32 s26, s6
	s_mov_b32 s27, s6
	v_readfirstlane_b32 s3, v0
	v_add_u32_e32 v0, v14, v12
	v_add_lshl_u32 v0, v0, v13, 1
	s_mul_i32 s2, s2, s3
	v_lshl_add_u64 v[134:135], s[12:13], 0, v[0:1]
	v_add_u32_e32 v0, v17, v15
	s_mul_hi_u32 s2, s3, s2
	v_add_lshl_u32 v0, v0, v16, 1
	s_bfe_i32 s66, s30, 0x1001c
	s_mov_b32 s30, 0
	s_add_i32 s71, s3, s2
	v_lshl_add_u64 v[140:141], s[12:13], 0, v[0:1]
	v_add_u32_e32 v151, 0, v20
	s_barrier
	s_branch .LBB0_1574

; #define PG8_STAGE(bufoff, gbase, voff) do { _Pragma("unroll") for (int _i = 0; _i < 2; ++_i) \
;         __builtin_amdgcn_global_load_lds((const unsigned*)((const char*)(gbase) + (voff)[_i]), (PG8_LAS unsigned*)(lds + (bufoff) + ldsw + _i * 8192), 16, 0, 0); } while (0)
; #define PG8_LDA(dst, b, h) do { _Pragma("unroll") for (int m = 0; m < 4; ++m) _Pragma("unroll") for (int k = 0; k < 2; ++k) dst[m][k] = *(const PG8_LAS bf16x8*)(lds + PG8_SA(b, h) + aoff + m * 2048 + k * 1024); } while (0)
; #define PG8_LDB(dst, b, h) do { _Pragma("unroll") for (int n = 0; n < 2; ++n) _Pragma("unroll") for (int k = 0; k < 2; ++k) dst[n][k] = *(const PG8_LAS bf16x8*)(lds + PG8_SB(b, h) + boff + n * 2048 + k * 1024); } while (0)
; #define PG8_MMA(ai, bj, At, Bt) do { __builtin_amdgcn_s_setprio(1); _Pragma("unroll") for (int m = 0; m < 4; ++m) _Pragma("unroll") for (int n = 0; n < 2; ++n) _Pragma("unroll") for (int k = 0; k < 2; ++k) \
;         acc[ai][bj][m][n] = __builtin_amdgcn_mfma_f32_16x16x32_bf16(Bt[n][k], At[m][k], acc[ai][bj][m][n], 0, 0, 0); __builtin_amdgcn_s_setprio(0); } while (0)
; #define PG8_WAIT_V(n) asm volatile("s_waitcnt vmcnt(" #n ")" ::: "memory")
; #define PG8_WAIT_L(n) asm volatile("s_waitcnt lgkmcnt(" #n ")" ::: "memory")
; #define PG8_BAR __builtin_amdgcn_s_barrier()
; #define PG8_SCHED __builtin_amdgcn_sched_barrier(0)
; template <class Epi, class Sched, bool ALIGN_EPI = false, bool SP2 = false>
; __device__ __forceinline__ void gemm_phase(PG8_LAS unsigned char* lds, const Gemm g, const Sched& S, const Epi& E, int tid_in) {
;     ...
;             PG8_LDB(B0, 0, 0); PG8_LDB(B1, 0, 1); PG8_SCHED; PG8_LDA(At, 0, 0); PG8_STAGE(PG8_SA(1, 1), a1 + hstep, voffA);
;             PG8_WAIT_V(8); PG8_WAIT_L(0); PG8_BAR; PG8_MMA(0, 0, At, B0); PG8_MMA(0, 1, At, B1); PG8_BAR; PG8_SCHED;
;             PG8_LDA(At, 0, 1); PG8_STAGE(PG8_SB(0, 0), b2, voffB); PG8_STAGE(PG8_SB(0, 1), b2 + hstep, voffB); PG8_STAGE(PG8_SA(0, 0), a2, voffA);
;             PG8_WAIT_V(8); PG8_WAIT_L(0); PG8_BAR; PG8_MMA(1, 0, At, B0); PG8_MMA(1, 1, At, B1); PG8_BAR; PG8_SCHED;
.LBB0_1582:
	s_add_i32 s81, s40, 2
	s_add_u32 s69, s38, 0x80
	s_addc_u32 s41, s39, 0
	s_add_i32 s83, 0, 0x10000
	s_cmp_eq_u32 s54, s40
	s_cselect_b32 s41, s5, s41
	s_cselect_b32 s40, s4, s69
	v_add_u32_e32 v139, s83, v150
	s_cselect_b32 s85, s37, s80
	s_cselect_b32 s84, s36, s33
	s_add_i32 s69, 0, 0x14000
	ds_read_b128 v[142:145], v139
	ds_read_b128 v[152:155], v139 offset:1024
	ds_read_b128 v[156:159], v139 offset:2048
	ds_read_b128 v[160:163], v139 offset:3072
	v_add_u32_e32 v139, s69, v150
	ds_read_b128 v[172:175], v139
	ds_read_b128 v[176:179], v139 offset:1024
	ds_read_b128 v[180:183], v139 offset:2048
	ds_read_b128 v[184:187], v139 offset:3072
	v_lshl_add_u64 v[146:147], s[38:39], 0, v[134:135]
	s_add_i32 m0, s29, 0xc000
	ds_read_b128 v[188:191], v151
	ds_read_b128 v[192:195], v151 offset:1024
	ds_read_b128 v[196:199], v151 offset:2048
	ds_read_b128 v[200:203], v151 offset:3072
	ds_read_b128 v[204:207], v151 offset:4096
	ds_read_b128 v[208:211], v151 offset:5120
	ds_read_b128 v[212:215], v151 offset:6144
	ds_read_b128 v[216:219], v151 offset:7168
	global_load_lds_dwordx4 v[146:147], off
	v_lshl_add_u64 v[146:147], s[38:39], 0, v[140:141]
	s_add_i32 m0, s29, 0xe000
	s_nop 0
	global_load_lds_dwordx4 v[146:147], off
	s_waitcnt vmcnt(8)
	s_waitcnt lgkmcnt(0)
	s_barrier
	s_setprio 1
	s_waitcnt lgkmcnt(0)
	v_mfma_f32_16x16x32_bf16 v[120:123], v[142:145], v[188:191], v[120:123]
	v_mfma_f32_16x16x32_bf16 v[124:127], v[156:159], v[188:191], v[124:127]
	v_mfma_f32_16x16x32_bf16 v[108:111], v[142:145], v[196:199], v[108:111]
	v_mfma_f32_16x16x32_bf16 v[104:107], v[156:159], v[196:199], v[104:107]
	v_mfma_f32_16x16x32_bf16 v[92:95], v[142:145], v[204:207], v[92:95]
	v_mfma_f32_16x16x32_bf16 v[88:91], v[156:159], v[204:207], v[88:91]
	v_mfma_f32_16x16x32_bf16 v[76:79], v[142:145], v[212:215], v[76:79]
	v_mfma_f32_16x16x32_bf16 v[72:75], v[156:159], v[212:215], v[72:75]
	v_mfma_f32_16x16x32_bf16 v[120:123], v[152:155], v[192:195], v[120:123]
	v_mfma_f32_16x16x32_bf16 v[124:127], v[160:163], v[192:195], v[124:127]
	v_mfma_f32_16x16x32_bf16 v[108:111], v[152:155], v[200:203], v[108:111]
	v_mfma_f32_16x16x32_bf16 v[104:107], v[160:163], v[200:203], v[104:107]
	v_mfma_f32_16x16x32_bf16 v[92:95], v[152:155], v[208:211], v[92:95]
	v_mfma_f32_16x16x32_bf16 v[88:91], v[160:163], v[208:211], v[88:91]
	v_mfma_f32_16x16x32_bf16 v[76:79], v[152:155], v[216:219], v[76:79]
	v_mfma_f32_16x16x32_bf16 v[72:75], v[160:163], v[216:219], v[72:75]
	s_setprio 0
	s_setprio 1
	v_mfma_f32_16x16x32_bf16 v[116:119], v[172:175], v[188:191], v[116:119]
	v_mfma_f32_16x16x32_bf16 v[112:115], v[180:183], v[188:191], v[112:115]
	v_mfma_f32_16x16x32_bf16 v[100:103], v[172:175], v[196:199], v[100:103]
	v_mfma_f32_16x16x32_bf16 v[96:99], v[180:183], v[196:199], v[96:99]
	v_mfma_f32_16x16x32_bf16 v[84:87], v[172:175], v[204:207], v[84:87]
	v_mfma_f32_16x16x32_bf16 v[80:83], v[180:183], v[204:207], v[80:83]
	v_mfma_f32_16x16x32_bf16 v[68:71], v[172:175], v[212:215], v[68:71]
	v_mfma_f32_16x16x32_bf16 v[64:67], v[180:183], v[212:215], v[64:67]
	v_mfma_f32_16x16x32_bf16 v[116:119], v[176:179], v[192:195], v[116:119]
	v_mfma_f32_16x16x32_bf16 v[112:115], v[184:187], v[192:195], v[112:115]
	v_mfma_f32_16x16x32_bf16 v[100:103], v[176:179], v[200:203], v[100:103]
	v_mfma_f32_16x16x32_bf16 v[96:99], v[184:187], v[200:203], v[96:99]
	v_mfma_f32_16x16x32_bf16 v[84:87], v[176:179], v[208:211], v[84:87]
	v_mfma_f32_16x16x32_bf16 v[80:83], v[184:187], v[208:211], v[80:83]
	v_mfma_f32_16x16x32_bf16 v[68:71], v[176:179], v[216:219], v[68:71]
	v_mfma_f32_16x16x32_bf16 v[64:67], v[184:187], v[216:219], v[64:67]
	s_setprio 0
	s_barrier
	s_add_i32 s83, s83, s28
	v_lshl_add_u64 v[146:147], s[84:85], 0, v[136:137]
	s_mov_b32 m0, s83
	ds_read_b128 v[188:191], v151 offset:16384
	ds_read_b128 v[192:195], v151 offset:17408
	ds_read_b128 v[196:199], v151 offset:18432
	ds_read_b128 v[200:203], v151 offset:19456
	ds_read_b128 v[204:207], v151 offset:20480
	ds_read_b128 v[208:211], v151 offset:21504
	ds_read_b128 v[212:215], v151 offset:22528
	ds_read_b128 v[216:219], v151 offset:23552
	global_load_lds_dwordx4 v[146:147], off
	s_add_i32 m0, s83, 0x2000
	v_lshl_add_u64 v[164:165], s[84:85], 0, v[132:133]
	s_add_u32 s84, s84, s12
	s_addc_u32 s85, s85, s13
	s_add_i32 s69, s69, s28
	global_load_lds_dwordx4 v[164:165], off
	v_lshl_add_u64 v[220:221], s[84:85], 0, v[136:137]
	s_mov_b32 m0, s69
	v_lshl_add_u64 v[222:223], s[84:85], 0, v[132:133]
	global_load_lds_dwordx4 v[220:221], off
	s_add_i32 m0, s69, 0x2000
	v_lshl_add_u64 v[224:225], s[40:41], 0, v[128:129]
	global_load_lds_dwordx4 v[222:223], off
	s_mov_b32 m0, s29
	v_lshl_add_u64 v[226:227], s[40:41], 0, v[130:131]
	global_load_lds_dwordx4 v[224:225], off
	s_mov_b32 m0, s34
	s_nop 0
	global_load_lds_dwordx4 v[226:227], off
	s_waitcnt vmcnt(8)
	s_waitcnt lgkmcnt(0)
	s_barrier
; #define PG8_STAGE(bufoff, gbase, voff) do { _Pragma("unroll") for (int _i = 0; _i < 2; ++_i) \
;         __builtin_amdgcn_global_load_lds((const unsigned*)((const char*)(gbase) + (voff)[_i]), (PG8_LAS unsigned*)(lds + (bufoff) + ldsw + _i * 8192), 16, 0, 0); } while (0)
; #define PG8_LDA(dst, b, h) do { _Pragma("unroll") for (int m = 0; m < 4; ++m) _Pragma("unroll") for (int k = 0; k < 2; ++k) dst[m][k] = *(const PG8_LAS bf16x8*)(lds + PG8_SA(b, h) + aoff + m * 2048 + k * 1024); } while (0)
; #define PG8_LDB(dst, b, h) do { _Pragma("unroll") for (int n = 0; n < 2; ++n) _Pragma("unroll") for (int k = 0; k < 2; ++k) dst[n][k] = *(const PG8_LAS bf16x8*)(lds + PG8_SB(b, h) + boff + n * 2048 + k * 1024); } while (0)
; #define PG8_MMA(ai, bj, At, Bt) do { __builtin_amdgcn_s_setprio(1); _Pragma("unroll") for (int m = 0; m < 4; ++m) _Pragma("unroll") for (int n = 0; n < 2; ++n) _Pragma("unroll") for (int k = 0; k < 2; ++k) \
;         acc[ai][bj][m][n] = __builtin_amdgcn_mfma_f32_16x16x32_bf16(Bt[n][k], At[m][k], acc[ai][bj][m][n], 0, 0, 0); __builtin_amdgcn_s_setprio(0); } while (0)
; #define PG8_WAIT_V(n) asm volatile("s_waitcnt vmcnt(" #n ")" ::: "memory")
; #define PG8_WAIT_L(n) asm volatile("s_waitcnt lgkmcnt(" #n ")" ::: "memory")
; #define PG8_BAR __builtin_amdgcn_s_barrier()
; #define PG8_SCHED __builtin_amdgcn_sched_barrier(0)
; template <class Epi, class Sched, bool ALIGN_EPI = false, bool SP2 = false>
; __device__ __forceinline__ void gemm_phase(PG8_LAS unsigned char* lds, const Gemm g, const Sched& S, const Epi& E, int tid_in) {
;     ...
;             PG8_WAIT_V(8); PG8_WAIT_L(0); PG8_BAR; PG8_MMA(1, 0, At, B0); PG8_MMA(1, 1, At, B1); PG8_BAR; PG8_SCHED;
;             PG8_LDB(B0, 1, 0); PG8_LDB(B1, 1, 1); PG8_SCHED; PG8_LDA(At, 1, 0); PG8_STAGE(PG8_SA(0, 1), a2 + hstep, voffA);
;             PG8_WAIT_V(8); PG8_WAIT_L(0); PG8_BAR; PG8_MMA(0, 0, At, B0); PG8_MMA(0, 1, At, B1); PG8_BAR; PG8_SCHED;
	s_setprio 1
	s_waitcnt lgkmcnt(0)
	v_mfma_f32_16x16x32_bf16 v[60:63], v[142:145], v[188:191], v[60:63]
	v_mfma_f32_16x16x32_bf16 v[56:59], v[156:159], v[188:191], v[56:59]
	v_mfma_f32_16x16x32_bf16 v[44:47], v[142:145], v[196:199], v[44:47]
	v_mfma_f32_16x16x32_bf16 v[40:43], v[156:159], v[196:199], v[40:43]
	v_mfma_f32_16x16x32_bf16 v[28:31], v[142:145], v[204:207], v[28:31]
	v_mfma_f32_16x16x32_bf16 v[24:27], v[156:159], v[204:207], v[24:27]
	v_mfma_f32_16x16x32_bf16 v[12:15], v[142:145], v[212:215], v[12:15]
	v_mfma_f32_16x16x32_bf16 v[8:11], v[156:159], v[212:215], v[8:11]
	v_mfma_f32_16x16x32_bf16 v[60:63], v[152:155], v[192:195], v[60:63]
	v_mfma_f32_16x16x32_bf16 v[56:59], v[160:163], v[192:195], v[56:59]
	v_mfma_f32_16x16x32_bf16 v[44:47], v[152:155], v[200:203], v[44:47]
	v_mfma_f32_16x16x32_bf16 v[40:43], v[160:163], v[200:203], v[40:43]
	v_mfma_f32_16x16x32_bf16 v[28:31], v[152:155], v[208:211], v[28:31]
	v_mfma_f32_16x16x32_bf16 v[24:27], v[160:163], v[208:211], v[24:27]
	v_mfma_f32_16x16x32_bf16 v[12:15], v[152:155], v[216:219], v[12:15]
	v_mfma_f32_16x16x32_bf16 v[8:11], v[160:163], v[216:219], v[8:11]
	s_setprio 0
	s_setprio 1
	v_mfma_f32_16x16x32_bf16 v[52:55], v[172:175], v[188:191], v[52:55]
	v_mfma_f32_16x16x32_bf16 v[48:51], v[180:183], v[188:191], v[48:51]
	v_mfma_f32_16x16x32_bf16 v[36:39], v[172:175], v[196:199], v[36:39]
	v_mfma_f32_16x16x32_bf16 v[32:35], v[180:183], v[196:199], v[32:35]
	v_mfma_f32_16x16x32_bf16 v[20:23], v[172:175], v[204:207], v[20:23]
	v_mfma_f32_16x16x32_bf16 v[16:19], v[180:183], v[204:207], v[16:19]
	v_mfma_f32_16x16x32_bf16 v[4:7], v[172:175], v[212:215], v[4:7]
	v_mfma_f32_16x16x32_bf16 v[0:3], v[180:183], v[212:215], v[0:3]
	v_mfma_f32_16x16x32_bf16 v[52:55], v[176:179], v[192:195], v[52:55]
	v_mfma_f32_16x16x32_bf16 v[48:51], v[184:187], v[192:195], v[48:51]
	v_mfma_f32_16x16x32_bf16 v[36:39], v[176:179], v[200:203], v[36:39]
	v_mfma_f32_16x16x32_bf16 v[32:35], v[184:187], v[200:203], v[32:35]
	v_mfma_f32_16x16x32_bf16 v[20:23], v[176:179], v[208:211], v[20:23]
	v_mfma_f32_16x16x32_bf16 v[16:19], v[184:187], v[208:211], v[16:19]
	v_mfma_f32_16x16x32_bf16 v[4:7], v[176:179], v[216:219], v[4:7]
	v_mfma_f32_16x16x32_bf16 v[0:3], v[184:187], v[216:219], v[0:3]
	s_setprio 0
	s_barrier
	s_add_i32 s69, 0, 0x18000
	v_add_u32_e32 v139, s69, v150
	s_add_i32 s83, 0, 0x1c000
	ds_read_b128 v[142:145], v139
	ds_read_b128 v[152:155], v139 offset:1024
	ds_read_b128 v[156:159], v139 offset:2048
	ds_read_b128 v[160:163], v139 offset:3072
	v_add_u32_e32 v139, s83, v150
	ds_read_b128 v[172:175], v139
	ds_read_b128 v[176:179], v139 offset:1024
	ds_read_b128 v[180:183], v139 offset:2048
	ds_read_b128 v[184:187], v139 offset:3072
	s_add_u32 s40, s40, s12
	s_addc_u32 s41, s41, s13
	s_mov_b32 m0, s42
	v_lshl_add_u64 v[228:229], s[40:41], 0, v[128:129]
	ds_read_b128 v[188:191], v151 offset:32768
	ds_read_b128 v[192:195], v151 offset:33792
	ds_read_b128 v[196:199], v151 offset:34816
	ds_read_b128 v[200:203], v151 offset:35840
	ds_read_b128 v[204:207], v151 offset:36864
	ds_read_b128 v[208:211], v151 offset:37888
	ds_read_b128 v[212:215], v151 offset:38912
	ds_read_b128 v[216:219], v151 offset:39936
	global_load_lds_dwordx4 v[228:229], off
	v_lshl_add_u64 v[228:229], s[40:41], 0, v[130:131]
	s_mov_b32 m0, s43
	s_nop 0
	global_load_lds_dwordx4 v[228:229], off
	s_waitcnt vmcnt(8)
	s_waitcnt lgkmcnt(0)
	s_barrier
	s_setprio 1
	s_waitcnt lgkmcnt(0)
	v_mfma_f32_16x16x32_bf16 v[120:123], v[142:145], v[188:191], v[120:123]
	v_mfma_f32_16x16x32_bf16 v[124:127], v[156:159], v[188:191], v[124:127]
	v_mfma_f32_16x16x32_bf16 v[108:111], v[142:145], v[196:199], v[108:111]
	v_mfma_f32_16x16x32_bf16 v[104:107], v[156:159], v[196:199], v[104:107]
	v_mfma_f32_16x16x32_bf16 v[92:95], v[142:145], v[204:207], v[92:95]
	v_mfma_f32_16x16x32_bf16 v[88:91], v[156:159], v[204:207], v[88:91]
	v_mfma_f32_16x16x32_bf16 v[76:79], v[142:145], v[212:215], v[76:79]
	v_mfma_f32_16x16x32_bf16 v[72:75], v[156:159], v[212:215], v[72:75]
	v_mfma_f32_16x16x32_bf16 v[120:123], v[152:155], v[192:195], v[120:123]
	v_mfma_f32_16x16x32_bf16 v[124:127], v[160:163], v[192:195], v[124:127]
	v_mfma_f32_16x16x32_bf16 v[108:111], v[152:155], v[200:203], v[108:111]
	v_mfma_f32_16x16x32_bf16 v[104:107], v[160:163], v[200:203], v[104:107]
	v_mfma_f32_16x16x32_bf16 v[92:95], v[152:155], v[208:211], v[92:95]
	v_mfma_f32_16x16x32_bf16 v[88:91], v[160:163], v[208:211], v[88:91]
	v_mfma_f32_16x16x32_bf16 v[76:79], v[152:155], v[216:219], v[76:79]
	v_mfma_f32_16x16x32_bf16 v[72:75], v[160:163], v[216:219], v[72:75]
	s_setprio 0
	s_setprio 1
	v_mfma_f32_16x16x32_bf16 v[116:119], v[172:175], v[188:191], v[116:119]
	v_mfma_f32_16x16x32_bf16 v[112:115], v[180:183], v[188:191], v[112:115]
	v_mfma_f32_16x16x32_bf16 v[100:103], v[172:175], v[196:199], v[100:103]
	v_mfma_f32_16x16x32_bf16 v[96:99], v[180:183], v[196:199], v[96:99]
	v_mfma_f32_16x16x32_bf16 v[84:87], v[172:175], v[204:207], v[84:87]
	v_mfma_f32_16x16x32_bf16 v[80:83], v[180:183], v[204:207], v[80:83]
	v_mfma_f32_16x16x32_bf16 v[68:71], v[172:175], v[212:215], v[68:71]
	v_mfma_f32_16x16x32_bf16 v[64:67], v[180:183], v[212:215], v[64:67]
	v_mfma_f32_16x16x32_bf16 v[116:119], v[176:179], v[192:195], v[116:119]
	v_mfma_f32_16x16x32_bf16 v[112:115], v[184:187], v[192:195], v[112:115]
	v_mfma_f32_16x16x32_bf16 v[100:103], v[176:179], v[200:203], v[100:103]
	v_mfma_f32_16x16x32_bf16 v[96:99], v[184:187], v[200:203], v[96:99]
	v_mfma_f32_16x16x32_bf16 v[84:87], v[176:179], v[208:211], v[84:87]
	v_mfma_f32_16x16x32_bf16 v[80:83], v[184:187], v[208:211], v[80:83]
	v_mfma_f32_16x16x32_bf16 v[68:71], v[176:179], v[216:219], v[68:71]
	v_mfma_f32_16x16x32_bf16 v[64:67], v[184:187], v[216:219], v[64:67]
	s_setprio 0
	s_barrier
; #define PG8_STAGE(bufoff, gbase, voff) do { _Pragma("unroll") for (int _i = 0; _i < 2; ++_i) \
;         __builtin_amdgcn_global_load_lds((const unsigned*)((const char*)(gbase) + (voff)[_i]), (PG8_LAS unsigned*)(lds + (bufoff) + ldsw + _i * 8192), 16, 0, 0); } while (0)
; #define PG8_LDA(dst, b, h) do { _Pragma("unroll") for (int m = 0; m < 4; ++m) _Pragma("unroll") for (int k = 0; k < 2; ++k) dst[m][k] = *(const PG8_LAS bf16x8*)(lds + PG8_SA(b, h) + aoff + m * 2048 + k * 1024); } while (0)
; #define PG8_MMA(ai, bj, At, Bt) do { __builtin_amdgcn_s_setprio(1); _Pragma("unroll") for (int m = 0; m < 4; ++m) _Pragma("unroll") for (int n = 0; n < 2; ++n) _Pragma("unroll") for (int k = 0; k < 2; ++k) \
;         acc[ai][bj][m][n] = __builtin_amdgcn_mfma_f32_16x16x32_bf16(Bt[n][k], At[m][k], acc[ai][bj][m][n], 0, 0, 0); __builtin_amdgcn_s_setprio(0); } while (0)
; #define PG8_WAIT_V(n) asm volatile("s_waitcnt vmcnt(" #n ")" ::: "memory")
; #define PG8_WAIT_L(n) asm volatile("s_waitcnt lgkmcnt(" #n ")" ::: "memory")
; #define PG8_BAR __builtin_amdgcn_s_barrier()
; #define PG8_SCHED __builtin_amdgcn_sched_barrier(0)
; template <class Epi, class Sched, bool ALIGN_EPI = false, bool SP2 = false>
; __device__ __forceinline__ void gemm_phase(PG8_LAS unsigned char* lds, const Gemm g, const Sched& S, const Epi& E, int tid_in) {
;     ...
;         for (int t = 0; t < nt; t += 2) {
;     ...
;             PG8_LDA(At, 1, 1); PG8_STAGE(PG8_SB(1, 0), b3, voffB); PG8_STAGE(PG8_SB(1, 1), b3 + hstep, voffB); PG8_STAGE(PG8_SA(1, 0), a3, voffA);
;             PG8_WAIT_V(8); PG8_WAIT_L(0); PG8_BAR; PG8_MMA(1, 0, At, B0); PG8_MMA(1, 1, At, B1); PG8_BAR; PG8_SCHED;
	s_add_i32 s40, s69, s28
	v_lshl_add_u64 v[146:147], v[146:147], 0, s[52:53]
	s_mov_b32 m0, s40
	ds_read_b128 v[188:191], v151 offset:49152
	ds_read_b128 v[192:195], v151 offset:50176
	ds_read_b128 v[196:199], v151 offset:51200
	ds_read_b128 v[200:203], v151 offset:52224
	ds_read_b128 v[204:207], v151 offset:53248
	ds_read_b128 v[208:211], v151 offset:54272
	ds_read_b128 v[212:215], v151 offset:55296
	ds_read_b128 v[216:219], v151 offset:56320
	global_load_lds_dwordx4 v[146:147], off
	v_lshl_add_u64 v[146:147], v[164:165], 0, s[52:53]
	s_add_i32 m0, s40, 0x2000
	s_add_i32 s40, s83, s28
	global_load_lds_dwordx4 v[146:147], off
	v_lshl_add_u64 v[146:147], v[220:221], 0, s[52:53]
	s_mov_b32 m0, s40
	s_nop 0
	global_load_lds_dwordx4 v[146:147], off
	v_lshl_add_u64 v[146:147], v[222:223], 0, s[52:53]
	s_add_i32 m0, s40, 0x2000
	s_nop 0
	global_load_lds_dwordx4 v[146:147], off
	v_lshl_add_u64 v[146:147], v[224:225], 0, s[52:53]
	s_mov_b32 m0, s48
	s_nop 0
	global_load_lds_dwordx4 v[146:147], off
	v_lshl_add_u64 v[146:147], v[226:227], 0, s[52:53]
	s_mov_b32 m0, s49
	s_nop 0
	global_load_lds_dwordx4 v[146:147], off
	s_waitcnt vmcnt(8)
	s_waitcnt lgkmcnt(0)
	s_barrier
	s_setprio 1
	s_waitcnt lgkmcnt(0)
	v_mfma_f32_16x16x32_bf16 v[60:63], v[142:145], v[188:191], v[60:63]
	v_mfma_f32_16x16x32_bf16 v[56:59], v[156:159], v[188:191], v[56:59]
	v_mfma_f32_16x16x32_bf16 v[44:47], v[142:145], v[196:199], v[44:47]
	v_mfma_f32_16x16x32_bf16 v[40:43], v[156:159], v[196:199], v[40:43]
	v_mfma_f32_16x16x32_bf16 v[28:31], v[142:145], v[204:207], v[28:31]
	v_mfma_f32_16x16x32_bf16 v[24:27], v[156:159], v[204:207], v[24:27]
	v_mfma_f32_16x16x32_bf16 v[12:15], v[142:145], v[212:215], v[12:15]
	v_mfma_f32_16x16x32_bf16 v[8:11], v[156:159], v[212:215], v[8:11]
	v_mfma_f32_16x16x32_bf16 v[60:63], v[152:155], v[192:195], v[60:63]
	v_mfma_f32_16x16x32_bf16 v[56:59], v[160:163], v[192:195], v[56:59]
	v_mfma_f32_16x16x32_bf16 v[44:47], v[152:155], v[200:203], v[44:47]
	v_mfma_f32_16x16x32_bf16 v[40:43], v[160:163], v[200:203], v[40:43]
	v_mfma_f32_16x16x32_bf16 v[28:31], v[152:155], v[208:211], v[28:31]
	v_mfma_f32_16x16x32_bf16 v[24:27], v[160:163], v[208:211], v[24:27]
	v_mfma_f32_16x16x32_bf16 v[12:15], v[152:155], v[216:219], v[12:15]
	v_mfma_f32_16x16x32_bf16 v[8:11], v[160:163], v[216:219], v[8:11]
	s_setprio 0
	s_setprio 1
	v_mfma_f32_16x16x32_bf16 v[52:55], v[172:175], v[188:191], v[52:55]
	v_mfma_f32_16x16x32_bf16 v[48:51], v[180:183], v[188:191], v[48:51]
	v_mfma_f32_16x16x32_bf16 v[36:39], v[172:175], v[196:199], v[36:39]
	v_mfma_f32_16x16x32_bf16 v[32:35], v[180:183], v[196:199], v[32:35]
	v_mfma_f32_16x16x32_bf16 v[20:23], v[172:175], v[204:207], v[20:23]
	v_mfma_f32_16x16x32_bf16 v[16:19], v[180:183], v[204:207], v[16:19]
	v_mfma_f32_16x16x32_bf16 v[4:7], v[172:175], v[212:215], v[4:7]
	v_mfma_f32_16x16x32_bf16 v[0:3], v[180:183], v[212:215], v[0:3]
	v_mfma_f32_16x16x32_bf16 v[52:55], v[176:179], v[192:195], v[52:55]
	v_mfma_f32_16x16x32_bf16 v[48:51], v[184:187], v[192:195], v[48:51]
	v_mfma_f32_16x16x32_bf16 v[36:39], v[176:179], v[200:203], v[36:39]
	v_mfma_f32_16x16x32_bf16 v[32:35], v[184:187], v[200:203], v[32:35]
	v_mfma_f32_16x16x32_bf16 v[20:23], v[176:179], v[208:211], v[20:23]
	v_mfma_f32_16x16x32_bf16 v[16:19], v[184:187], v[208:211], v[16:19]
	v_mfma_f32_16x16x32_bf16 v[4:7], v[176:179], v[216:219], v[4:7]
	v_mfma_f32_16x16x32_bf16 v[0:3], v[184:187], v[216:219], v[0:3]
	s_add_u32 s38, s38, 0x100
	s_addc_u32 s39, s39, 0
	s_add_u32 s33, s33, 0x100
	s_addc_u32 s80, s80, 0
	s_cmp_ge_i32 s81, s45
	s_mov_b32 s40, s81
	s_setprio 0
	s_barrier
	s_cbranch_scc0 .LBB0_1582
